# one static s_setprio 1 for waves 0-3 in front of every K-loop (s_setprio 0 behind it), on top of v76
# baseline (speedup 1.0000x reference)
.LBB0_123:
	s_lshl_b32 s3, s43, 20
	s_and_b64 s[6:7], s[4:5], exec
	s_cselect_b32 s6, s3, s10
	s_lshl_b32 s88, s46, 20
	s_and_b64 s[12:13], s[4:5], exec
	s_cselect_b32 s7, s88, s11
	s_add_i32 s8, s9, -2
	s_lshl_b32 s9, s9, 7
	s_addk_i32 s11, 0x100
	s_movk_i32 s12, 0xf00
	v_readfirstlane_b32 s98, v0
	s_nop 0
	s_bitcmp0_b32 s98, 8
	s_cbranch_scc0 .Lprio_0
	s_setprio 1
.Lprio_0:
.LBB0_124:
	ds_read_b128 v[138:141], v151
	ds_read_b128 v[142:145], v151 offset:1024
	ds_read_b128 v[158:161], v151 offset:2048
	ds_read_b128 v[162:165], v151 offset:3072
	ds_read_b128 v[166:169], v152
	ds_read_b128 v[170:173], v152 offset:1024
	ds_read_b128 v[174:177], v152 offset:2048
	ds_read_b128 v[178:181], v152 offset:3072
	s_add_i32 s47, s9, s10
	s_add_i32 s75, s47, 0x100
	s_add_i32 s13, s9, s11
	s_cmp_eq_u32 s9, s12
	s_cselect_b32 s13, s7, s13
	s_cselect_b32 s80, s6, s75
	s_add_i32 s75, s47, 0x80
	s_mov_b32 m0, s58
	ds_read_b128 v[182:185], v153
	ds_read_b128 v[186:189], v153 offset:1024
	buffer_load_dwordx4 v1, s[28:31], s75 offen lds
	s_mov_b32 m0, s59
	ds_read_b128 v[190:193], v153 offset:2048
	ds_read_b128 v[194:197], v153 offset:3072
	buffer_load_dwordx4 v147, s[28:31], s75 offen lds
	s_add_i32 s47, s47, 0x80080
	s_mov_b32 m0, s70
	ds_read_b128 v[198:201], v153 offset:4096
	ds_read_b128 v[202:205], v153 offset:5120
	buffer_load_dwordx4 v1, s[28:31], s47 offen lds
	s_mov_b32 m0, s71
	ds_read_b128 v[206:209], v153 offset:6144
	ds_read_b128 v[210:213], v153 offset:7168
	buffer_load_dwordx4 v147, s[28:31], s47 offen lds
	s_waitcnt vmcnt(8)
	s_waitcnt lgkmcnt(0)
	s_barrier
	s_waitcnt lgkmcnt(0)
	v_mfma_f32_16x16x32_bf16 v[130:133], v[138:141], v[182:185], v[130:133]
	v_mfma_f32_16x16x32_bf16 v[130:133], v[142:145], v[186:189], v[130:133]
	v_mfma_f32_16x16x32_bf16 v[114:117], v[142:145], v[194:197], v[114:117]
	v_mfma_f32_16x16x32_bf16 v[114:117], v[138:141], v[190:193], v[114:117]
	v_mfma_f32_16x16x32_bf16 v[98:101], v[138:141], v[198:201], v[98:101]
	v_mfma_f32_16x16x32_bf16 v[98:101], v[142:145], v[202:205], v[98:101]
	v_mfma_f32_16x16x32_bf16 v[82:85], v[142:145], v[210:213], v[82:85]
	v_mfma_f32_16x16x32_bf16 v[82:85], v[138:141], v[206:209], v[82:85]
	v_mfma_f32_16x16x32_bf16 v[78:81], v[162:165], v[210:213], v[78:81]
	v_mfma_f32_16x16x32_bf16 v[78:81], v[158:161], v[206:209], v[78:81]
	v_mfma_f32_16x16x32_bf16 v[94:97], v[158:161], v[198:201], v[94:97]
	v_mfma_f32_16x16x32_bf16 v[94:97], v[162:165], v[202:205], v[94:97]
	v_mfma_f32_16x16x32_bf16 v[110:113], v[162:165], v[194:197], v[110:113]
	v_mfma_f32_16x16x32_bf16 v[110:113], v[158:161], v[190:193], v[110:113]
	v_mfma_f32_16x16x32_bf16 v[126:129], v[158:161], v[182:185], v[126:129]
	v_mfma_f32_16x16x32_bf16 v[126:129], v[162:165], v[186:189], v[126:129]
	v_mfma_f32_16x16x32_bf16 v[122:125], v[166:169], v[182:185], v[122:125]
	v_mfma_f32_16x16x32_bf16 v[122:125], v[170:173], v[186:189], v[122:125]
	v_mfma_f32_16x16x32_bf16 v[106:109], v[170:173], v[194:197], v[106:109]
	v_mfma_f32_16x16x32_bf16 v[106:109], v[166:169], v[190:193], v[106:109]
	v_mfma_f32_16x16x32_bf16 v[90:93], v[166:169], v[198:201], v[90:93]
	v_mfma_f32_16x16x32_bf16 v[90:93], v[170:173], v[202:205], v[90:93]
	v_mfma_f32_16x16x32_bf16 v[74:77], v[170:173], v[210:213], v[74:77]
	v_mfma_f32_16x16x32_bf16 v[74:77], v[166:169], v[206:209], v[74:77]
	v_mfma_f32_16x16x32_bf16 v[70:73], v[178:181], v[210:213], v[70:73]
	v_mfma_f32_16x16x32_bf16 v[70:73], v[174:177], v[206:209], v[70:73]
	v_mfma_f32_16x16x32_bf16 v[86:89], v[174:177], v[198:201], v[86:89]
	v_mfma_f32_16x16x32_bf16 v[86:89], v[178:181], v[202:205], v[86:89]
	v_mfma_f32_16x16x32_bf16 v[102:105], v[178:181], v[194:197], v[102:105]
	v_mfma_f32_16x16x32_bf16 v[102:105], v[174:177], v[190:193], v[102:105]
	v_mfma_f32_16x16x32_bf16 v[118:121], v[174:177], v[182:185], v[118:121]
	v_mfma_f32_16x16x32_bf16 v[118:121], v[178:181], v[186:189], v[118:121]
	s_barrier
	s_mov_b32 m0, s91
	s_mov_b32 s75, s31
	ds_read_b128 v[182:185], v153 offset:16384
	ds_read_b128 v[186:189], v153 offset:17408
	buffer_load_dwordx4 v146, s[72:75], s13 offen lds
	s_mov_b32 m0, s93
	ds_read_b128 v[190:193], v153 offset:18432
	ds_read_b128 v[194:197], v153 offset:19456
	buffer_load_dwordx4 v148, s[72:75], s13 offen lds
	s_add_i32 s47, s13, 0x80000
	s_mov_b32 m0, s95
	ds_read_b128 v[198:201], v153 offset:20480
	ds_read_b128 v[202:205], v153 offset:21504
	buffer_load_dwordx4 v146, s[72:75], s47 offen lds
	s_mov_b32 m0, s35
	ds_read_b128 v[206:209], v153 offset:22528
	ds_read_b128 v[210:213], v153 offset:23552
	buffer_load_dwordx4 v148, s[72:75], s47 offen lds
	s_waitcnt vmcnt(6)
	s_waitcnt lgkmcnt(0)
	s_barrier
	s_waitcnt lgkmcnt(0)
	v_mfma_f32_16x16x32_bf16 v[66:69], v[138:141], v[182:185], v[66:69]
	v_mfma_f32_16x16x32_bf16 v[66:69], v[142:145], v[186:189], v[66:69]
	v_mfma_f32_16x16x32_bf16 v[50:53], v[142:145], v[194:197], v[50:53]
	v_mfma_f32_16x16x32_bf16 v[50:53], v[138:141], v[190:193], v[50:53]
	v_mfma_f32_16x16x32_bf16 v[34:37], v[138:141], v[198:201], v[34:37]
	v_mfma_f32_16x16x32_bf16 v[34:37], v[142:145], v[202:205], v[34:37]
	v_mfma_f32_16x16x32_bf16 v[18:21], v[142:145], v[210:213], v[18:21]
	v_mfma_f32_16x16x32_bf16 v[18:21], v[138:141], v[206:209], v[18:21]
	v_mfma_f32_16x16x32_bf16 v[14:17], v[162:165], v[210:213], v[14:17]
	v_mfma_f32_16x16x32_bf16 v[14:17], v[158:161], v[206:209], v[14:17]
	v_mfma_f32_16x16x32_bf16 v[30:33], v[158:161], v[198:201], v[30:33]
	v_mfma_f32_16x16x32_bf16 v[30:33], v[162:165], v[202:205], v[30:33]
	v_mfma_f32_16x16x32_bf16 v[46:49], v[162:165], v[194:197], v[46:49]
	v_mfma_f32_16x16x32_bf16 v[46:49], v[158:161], v[190:193], v[46:49]
	v_mfma_f32_16x16x32_bf16 v[62:65], v[158:161], v[182:185], v[62:65]
	v_mfma_f32_16x16x32_bf16 v[62:65], v[162:165], v[186:189], v[62:65]
	v_mfma_f32_16x16x32_bf16 v[58:61], v[166:169], v[182:185], v[58:61]
	v_mfma_f32_16x16x32_bf16 v[58:61], v[170:173], v[186:189], v[58:61]
	v_mfma_f32_16x16x32_bf16 v[42:45], v[170:173], v[194:197], v[42:45]
	v_mfma_f32_16x16x32_bf16 v[42:45], v[166:169], v[190:193], v[42:45]
	v_mfma_f32_16x16x32_bf16 v[26:29], v[166:169], v[198:201], v[26:29]
	v_mfma_f32_16x16x32_bf16 v[26:29], v[170:173], v[202:205], v[26:29]
	v_mfma_f32_16x16x32_bf16 v[10:13], v[170:173], v[210:213], v[10:13]
	v_mfma_f32_16x16x32_bf16 v[10:13], v[166:169], v[206:209], v[10:13]
	v_mfma_f32_16x16x32_bf16 v[4:7], v[174:177], v[206:209], v[6:9]
	v_mfma_f32_16x16x32_bf16 v[4:7], v[178:181], v[210:213], v[4:7]
	v_mfma_f32_16x16x32_bf16 v[22:25], v[174:177], v[198:201], v[22:25]
	v_mfma_f32_16x16x32_bf16 v[22:25], v[178:181], v[202:205], v[22:25]
	v_mfma_f32_16x16x32_bf16 v[38:41], v[178:181], v[194:197], v[38:41]
	v_mfma_f32_16x16x32_bf16 v[38:41], v[174:177], v[190:193], v[38:41]
	v_mfma_f32_16x16x32_bf16 v[54:57], v[174:177], v[182:185], v[54:57]
	v_mfma_f32_16x16x32_bf16 v[54:57], v[178:181], v[186:189], v[54:57]
	s_barrier
	ds_read_b128 v[138:141], v154
	ds_read_b128 v[142:145], v154 offset:1024
	ds_read_b128 v[158:161], v154 offset:2048
	ds_read_b128 v[162:165], v154 offset:3072
	ds_read_b128 v[166:169], v155
	ds_read_b128 v[170:173], v155 offset:1024
	ds_read_b128 v[174:177], v155 offset:2048
	ds_read_b128 v[178:181], v155 offset:3072
	s_mov_b32 m0, s77
	ds_read_b128 v[182:185], v153 offset:32768
	ds_read_b128 v[186:189], v153 offset:33792
	buffer_load_dwordx4 v1, s[28:31], s80 offen lds
	s_mov_b32 m0, s84
	ds_read_b128 v[190:193], v153 offset:34816
	ds_read_b128 v[194:197], v153 offset:35840
	buffer_load_dwordx4 v147, s[28:31], s80 offen lds
	s_add_i32 s80, s80, 0x80000
	s_mov_b32 m0, s85
	ds_read_b128 v[198:201], v153 offset:36864
	ds_read_b128 v[202:205], v153 offset:37888
	buffer_load_dwordx4 v1, s[28:31], s80 offen lds
	s_mov_b32 m0, s48
	ds_read_b128 v[206:209], v153 offset:38912
	ds_read_b128 v[210:213], v153 offset:39936
	buffer_load_dwordx4 v147, s[28:31], s80 offen lds
	s_waitcnt vmcnt(8)
	s_waitcnt lgkmcnt(0)
	s_barrier
	s_waitcnt lgkmcnt(0)
	v_mfma_f32_16x16x32_bf16 v[130:133], v[138:141], v[182:185], v[130:133]
	v_mfma_f32_16x16x32_bf16 v[130:133], v[142:145], v[186:189], v[130:133]
	v_mfma_f32_16x16x32_bf16 v[114:117], v[142:145], v[194:197], v[114:117]
	v_mfma_f32_16x16x32_bf16 v[114:117], v[138:141], v[190:193], v[114:117]
	v_mfma_f32_16x16x32_bf16 v[98:101], v[138:141], v[198:201], v[98:101]
	v_mfma_f32_16x16x32_bf16 v[98:101], v[142:145], v[202:205], v[98:101]
	v_mfma_f32_16x16x32_bf16 v[82:85], v[142:145], v[210:213], v[82:85]
	v_mfma_f32_16x16x32_bf16 v[82:85], v[138:141], v[206:209], v[82:85]
	v_mfma_f32_16x16x32_bf16 v[78:81], v[162:165], v[210:213], v[78:81]
	v_mfma_f32_16x16x32_bf16 v[78:81], v[158:161], v[206:209], v[78:81]
	v_mfma_f32_16x16x32_bf16 v[94:97], v[158:161], v[198:201], v[94:97]
	v_mfma_f32_16x16x32_bf16 v[94:97], v[162:165], v[202:205], v[94:97]
	v_mfma_f32_16x16x32_bf16 v[110:113], v[162:165], v[194:197], v[110:113]
	v_mfma_f32_16x16x32_bf16 v[110:113], v[158:161], v[190:193], v[110:113]
	v_mfma_f32_16x16x32_bf16 v[126:129], v[158:161], v[182:185], v[126:129]
	v_mfma_f32_16x16x32_bf16 v[126:129], v[162:165], v[186:189], v[126:129]
	v_mfma_f32_16x16x32_bf16 v[122:125], v[166:169], v[182:185], v[122:125]
	v_mfma_f32_16x16x32_bf16 v[122:125], v[170:173], v[186:189], v[122:125]
	v_mfma_f32_16x16x32_bf16 v[106:109], v[170:173], v[194:197], v[106:109]
	v_mfma_f32_16x16x32_bf16 v[106:109], v[166:169], v[190:193], v[106:109]
	v_mfma_f32_16x16x32_bf16 v[90:93], v[166:169], v[198:201], v[90:93]
	v_mfma_f32_16x16x32_bf16 v[90:93], v[170:173], v[202:205], v[90:93]
	v_mfma_f32_16x16x32_bf16 v[74:77], v[170:173], v[210:213], v[74:77]
	v_mfma_f32_16x16x32_bf16 v[74:77], v[166:169], v[206:209], v[74:77]
	v_mfma_f32_16x16x32_bf16 v[70:73], v[178:181], v[210:213], v[70:73]
	v_mfma_f32_16x16x32_bf16 v[70:73], v[174:177], v[206:209], v[70:73]
	v_mfma_f32_16x16x32_bf16 v[86:89], v[174:177], v[198:201], v[86:89]
	v_mfma_f32_16x16x32_bf16 v[86:89], v[178:181], v[202:205], v[86:89]
	v_mfma_f32_16x16x32_bf16 v[102:105], v[178:181], v[194:197], v[102:105]
	v_mfma_f32_16x16x32_bf16 v[102:105], v[174:177], v[190:193], v[102:105]
	v_mfma_f32_16x16x32_bf16 v[118:121], v[174:177], v[182:185], v[118:121]
	v_mfma_f32_16x16x32_bf16 v[118:121], v[178:181], v[186:189], v[118:121]
	s_barrier
	s_mov_b32 m0, s78
	s_add_i32 s47, s13, 0x80
	ds_read_b128 v[182:185], v153 offset:49152
	ds_read_b128 v[186:189], v153 offset:50176
	buffer_load_dwordx4 v146, s[72:75], s47 offen lds
	s_mov_b32 m0, s79
	ds_read_b128 v[190:193], v153 offset:51200
	ds_read_b128 v[194:197], v153 offset:52224
	buffer_load_dwordx4 v148, s[72:75], s47 offen lds
	s_add_i32 s13, s13, 0x80080
	s_mov_b32 m0, s86
	ds_read_b128 v[198:201], v153 offset:53248
	ds_read_b128 v[202:205], v153 offset:54272
	buffer_load_dwordx4 v146, s[72:75], s13 offen lds
	s_mov_b32 m0, s87
	ds_read_b128 v[206:209], v153 offset:55296
	ds_read_b128 v[210:213], v153 offset:56320
	buffer_load_dwordx4 v148, s[72:75], s13 offen lds
	s_waitcnt vmcnt(6)
	s_waitcnt lgkmcnt(0)
	s_barrier
	s_waitcnt lgkmcnt(0)
	v_mfma_f32_16x16x32_bf16 v[66:69], v[138:141], v[182:185], v[66:69]
	v_mfma_f32_16x16x32_bf16 v[66:69], v[142:145], v[186:189], v[66:69]
	v_mfma_f32_16x16x32_bf16 v[50:53], v[142:145], v[194:197], v[50:53]
	v_mfma_f32_16x16x32_bf16 v[50:53], v[138:141], v[190:193], v[50:53]
	v_mfma_f32_16x16x32_bf16 v[34:37], v[138:141], v[198:201], v[34:37]
	v_mfma_f32_16x16x32_bf16 v[34:37], v[142:145], v[202:205], v[34:37]
	v_mfma_f32_16x16x32_bf16 v[18:21], v[142:145], v[210:213], v[18:21]
	v_mfma_f32_16x16x32_bf16 v[18:21], v[138:141], v[206:209], v[18:21]
	v_mfma_f32_16x16x32_bf16 v[14:17], v[162:165], v[210:213], v[14:17]
	v_mfma_f32_16x16x32_bf16 v[14:17], v[158:161], v[206:209], v[14:17]
	v_mfma_f32_16x16x32_bf16 v[30:33], v[158:161], v[198:201], v[30:33]
	v_mfma_f32_16x16x32_bf16 v[30:33], v[162:165], v[202:205], v[30:33]
	v_mfma_f32_16x16x32_bf16 v[46:49], v[162:165], v[194:197], v[46:49]
	v_mfma_f32_16x16x32_bf16 v[46:49], v[158:161], v[190:193], v[46:49]
	v_mfma_f32_16x16x32_bf16 v[62:65], v[158:161], v[182:185], v[62:65]
	v_mfma_f32_16x16x32_bf16 v[62:65], v[162:165], v[186:189], v[62:65]
	v_mfma_f32_16x16x32_bf16 v[58:61], v[166:169], v[182:185], v[58:61]
	v_mfma_f32_16x16x32_bf16 v[58:61], v[170:173], v[186:189], v[58:61]
	v_mfma_f32_16x16x32_bf16 v[42:45], v[170:173], v[194:197], v[42:45]
	v_mfma_f32_16x16x32_bf16 v[42:45], v[166:169], v[190:193], v[42:45]
	v_mfma_f32_16x16x32_bf16 v[26:29], v[166:169], v[198:201], v[26:29]
	v_mfma_f32_16x16x32_bf16 v[26:29], v[170:173], v[202:205], v[26:29]
	v_mfma_f32_16x16x32_bf16 v[8:11], v[166:169], v[206:209], v[10:13]
	v_mfma_f32_16x16x32_bf16 v[10:13], v[170:173], v[210:213], v[8:11]
	v_mfma_f32_16x16x32_bf16 v[4:7], v[174:177], v[206:209], v[4:7]
	v_mfma_f32_16x16x32_bf16 v[6:9], v[178:181], v[210:213], v[4:7]
	v_mfma_f32_16x16x32_bf16 v[22:25], v[174:177], v[198:201], v[22:25]
	v_mfma_f32_16x16x32_bf16 v[22:25], v[178:181], v[202:205], v[22:25]
	v_mfma_f32_16x16x32_bf16 v[38:41], v[178:181], v[194:197], v[38:41]
	v_mfma_f32_16x16x32_bf16 v[38:41], v[174:177], v[190:193], v[38:41]
	v_mfma_f32_16x16x32_bf16 v[54:57], v[174:177], v[182:185], v[54:57]
	v_mfma_f32_16x16x32_bf16 v[54:57], v[178:181], v[186:189], v[54:57]
	s_barrier
	s_add_i32 s8, s8, 2
	s_addk_i32 s10, 0x100
	s_addk_i32 s11, 0x100
	s_addk_i32 s12, 0xff00
	s_cmp_gt_u32 s8, 29
	s_cbranch_scc0 .LBB0_124
	s_setprio 0
	v_readlane_b32 s6, v254, 26
	v_readlane_b32 s7, v254, 27
	s_and_b64 vcc, exec, s[6:7]
	s_cbranch_vccz .LBB0_127
	s_barrier

.LBB0_526:
	s_and_b64 s[62:63], s[62:63], exec
	s_cselect_b32 s62, 48, s98
	s_cmp_eq_u32 s92, s62
	s_cbranch_scc1 .LBB0_523
	s_cmp_eq_u32 s92, 0
	s_cselect_b32 s63, 0, s99
	s_cselect_b32 s93, s100, s101
	s_mov_b32 s94, s88
	s_mov_b32 s95, s91
	v_readfirstlane_b32 s71, v0
	s_nop 0
	s_bitcmp0_b32 s71, 8
	s_cbranch_scc0 .Lprio_1
	s_setprio 1
.Lprio_1:
.LBB0_528:
	v_add_u32_e32 v3, 0x10000, v171
	ds_read_b128 v[134:137], v3
	ds_read_b128 v[138:141], v3 offset:1024
	ds_read_b128 v[142:145], v3 offset:2048
	ds_read_b128 v[146:149], v3 offset:3072
	v_add_u32_e32 v3, 0x14000, v171
	ds_read_b128 v[150:153], v3
	ds_read_b128 v[154:157], v3 offset:1024
	ds_read_b128 v[174:177], v3 offset:2048
	ds_read_b128 v[178:181], v3 offset:3072
	s_add_i32 s71, s63, s94
	s_add_i32 s97, s71, 0x100
	s_add_i32 s96, s63, s95
	s_cmp_eq_u32 s63, s93
	s_cselect_b32 s96, s90, s96
	s_cselect_b32 s97, s89, s97
	s_add_i32 vcc_lo, s71, 0x80
	s_mov_b32 m0, s79
	ds_read_b128 v[182:185], v172
	ds_read_b128 v[186:189], v172 offset:1024
	buffer_load_dwordx4 v1, s[48:51], vcc_lo offen lds
	s_mov_b32 m0, s80
	ds_read_b128 v[190:193], v172 offset:2048
	ds_read_b128 v[194:197], v172 offset:3072
	buffer_load_dwordx4 v167, s[48:51], vcc_lo offen lds
	s_add_i32 s71, s71, 0xc0080
	s_mov_b32 m0, s81
	ds_read_b128 v[198:201], v172 offset:4096
	ds_read_b128 v[202:205], v172 offset:5120
	buffer_load_dwordx4 v1, s[48:51], s71 offen lds
	s_mov_b32 m0, s82
	ds_read_b128 v[206:209], v172 offset:6144
	ds_read_b128 v[210:213], v172 offset:7168
	buffer_load_dwordx4 v167, s[48:51], s71 offen lds
	s_waitcnt vmcnt(8)
	s_waitcnt lgkmcnt(0)
	s_barrier
	s_waitcnt lgkmcnt(0)
	v_mfma_f32_16x16x32_bf16 v[130:133], v[134:137], v[182:185], v[130:133]
	v_mfma_f32_16x16x32_bf16 v[130:133], v[138:141], v[186:189], v[130:133]
	v_mfma_f32_16x16x32_bf16 v[114:117], v[138:141], v[194:197], v[114:117]
	v_mfma_f32_16x16x32_bf16 v[114:117], v[134:137], v[190:193], v[114:117]
	v_mfma_f32_16x16x32_bf16 v[98:101], v[134:137], v[198:201], v[98:101]
	v_mfma_f32_16x16x32_bf16 v[98:101], v[138:141], v[202:205], v[98:101]
	v_mfma_f32_16x16x32_bf16 v[82:85], v[138:141], v[210:213], v[82:85]
	v_mfma_f32_16x16x32_bf16 v[82:85], v[134:137], v[206:209], v[82:85]
	v_mfma_f32_16x16x32_bf16 v[78:81], v[146:149], v[210:213], v[78:81]
	v_mfma_f32_16x16x32_bf16 v[78:81], v[142:145], v[206:209], v[78:81]
	v_mfma_f32_16x16x32_bf16 v[94:97], v[142:145], v[198:201], v[94:97]
	v_mfma_f32_16x16x32_bf16 v[94:97], v[146:149], v[202:205], v[94:97]
	v_mfma_f32_16x16x32_bf16 v[110:113], v[146:149], v[194:197], v[110:113]
	v_mfma_f32_16x16x32_bf16 v[110:113], v[142:145], v[190:193], v[110:113]
	v_mfma_f32_16x16x32_bf16 v[126:129], v[142:145], v[182:185], v[126:129]
	v_mfma_f32_16x16x32_bf16 v[126:129], v[146:149], v[186:189], v[126:129]
	v_mfma_f32_16x16x32_bf16 v[122:125], v[150:153], v[182:185], v[122:125]
	v_mfma_f32_16x16x32_bf16 v[122:125], v[154:157], v[186:189], v[122:125]
	v_mfma_f32_16x16x32_bf16 v[106:109], v[154:157], v[194:197], v[106:109]
	v_mfma_f32_16x16x32_bf16 v[106:109], v[150:153], v[190:193], v[106:109]
	v_mfma_f32_16x16x32_bf16 v[90:93], v[150:153], v[198:201], v[90:93]
	v_mfma_f32_16x16x32_bf16 v[90:93], v[154:157], v[202:205], v[90:93]
	v_mfma_f32_16x16x32_bf16 v[74:77], v[154:157], v[210:213], v[74:77]
	v_mfma_f32_16x16x32_bf16 v[74:77], v[150:153], v[206:209], v[74:77]
	v_mfma_f32_16x16x32_bf16 v[70:73], v[178:181], v[210:213], v[70:73]
	v_mfma_f32_16x16x32_bf16 v[70:73], v[174:177], v[206:209], v[70:73]
	v_mfma_f32_16x16x32_bf16 v[86:89], v[174:177], v[198:201], v[86:89]
	v_mfma_f32_16x16x32_bf16 v[86:89], v[178:181], v[202:205], v[86:89]
	v_mfma_f32_16x16x32_bf16 v[102:105], v[178:181], v[194:197], v[102:105]
	v_mfma_f32_16x16x32_bf16 v[102:105], v[174:177], v[190:193], v[102:105]
	v_mfma_f32_16x16x32_bf16 v[118:121], v[174:177], v[182:185], v[118:121]
	v_mfma_f32_16x16x32_bf16 v[118:121], v[178:181], v[186:189], v[118:121]
	s_barrier
	s_mov_b32 m0, s35
	s_mov_b32 s71, s51
	ds_read_b128 v[182:185], v172 offset:16384
	ds_read_b128 v[186:189], v172 offset:17408
	buffer_load_dwordx4 v166, s[68:71], s96 offen lds
	s_mov_b32 m0, s45
	ds_read_b128 v[190:193], v172 offset:18432
	ds_read_b128 v[194:197], v172 offset:19456
	buffer_load_dwordx4 v168, s[68:71], s96 offen lds
	s_add_i32 vcc_lo, s96, 0xc0000
	s_mov_b32 m0, s64
	ds_read_b128 v[198:201], v172 offset:20480
	ds_read_b128 v[202:205], v172 offset:21504
	buffer_load_dwordx4 v166, s[68:71], vcc_lo offen lds
	s_mov_b32 m0, s65
	ds_read_b128 v[206:209], v172 offset:22528
	ds_read_b128 v[210:213], v172 offset:23552
	buffer_load_dwordx4 v168, s[68:71], vcc_lo offen lds
	s_waitcnt vmcnt(6)
	s_waitcnt lgkmcnt(0)
	s_barrier
	s_waitcnt lgkmcnt(0)
	v_mfma_f32_16x16x32_bf16 v[66:69], v[134:137], v[182:185], v[66:69]
	v_mfma_f32_16x16x32_bf16 v[66:69], v[138:141], v[186:189], v[66:69]
	v_mfma_f32_16x16x32_bf16 v[50:53], v[138:141], v[194:197], v[50:53]
	v_mfma_f32_16x16x32_bf16 v[50:53], v[134:137], v[190:193], v[50:53]
	v_mfma_f32_16x16x32_bf16 v[34:37], v[134:137], v[198:201], v[34:37]
	v_mfma_f32_16x16x32_bf16 v[34:37], v[138:141], v[202:205], v[34:37]
	v_mfma_f32_16x16x32_bf16 v[18:21], v[138:141], v[210:213], v[18:21]
	v_mfma_f32_16x16x32_bf16 v[18:21], v[134:137], v[206:209], v[18:21]
	v_mfma_f32_16x16x32_bf16 v[14:17], v[146:149], v[210:213], v[14:17]
	v_mfma_f32_16x16x32_bf16 v[14:17], v[142:145], v[206:209], v[14:17]
	v_mfma_f32_16x16x32_bf16 v[30:33], v[142:145], v[198:201], v[30:33]
	v_mfma_f32_16x16x32_bf16 v[30:33], v[146:149], v[202:205], v[30:33]
	v_mfma_f32_16x16x32_bf16 v[46:49], v[146:149], v[194:197], v[46:49]
	v_mfma_f32_16x16x32_bf16 v[46:49], v[142:145], v[190:193], v[46:49]
	v_mfma_f32_16x16x32_bf16 v[62:65], v[142:145], v[182:185], v[62:65]
	v_mfma_f32_16x16x32_bf16 v[62:65], v[146:149], v[186:189], v[62:65]
	v_mfma_f32_16x16x32_bf16 v[58:61], v[150:153], v[182:185], v[58:61]
	v_mfma_f32_16x16x32_bf16 v[58:61], v[154:157], v[186:189], v[58:61]
	v_mfma_f32_16x16x32_bf16 v[42:45], v[154:157], v[194:197], v[42:45]
	v_mfma_f32_16x16x32_bf16 v[42:45], v[150:153], v[190:193], v[42:45]
	v_mfma_f32_16x16x32_bf16 v[26:29], v[150:153], v[198:201], v[26:29]
	v_mfma_f32_16x16x32_bf16 v[26:29], v[154:157], v[202:205], v[26:29]
	v_mfma_f32_16x16x32_bf16 v[10:13], v[154:157], v[210:213], v[10:13]
	v_mfma_f32_16x16x32_bf16 v[10:13], v[150:153], v[206:209], v[10:13]
	v_mfma_f32_16x16x32_bf16 v[4:7], v[174:177], v[206:209], v[6:9]
	v_mfma_f32_16x16x32_bf16 v[4:7], v[178:181], v[210:213], v[4:7]
	v_mfma_f32_16x16x32_bf16 v[22:25], v[174:177], v[198:201], v[22:25]
	v_mfma_f32_16x16x32_bf16 v[22:25], v[178:181], v[202:205], v[22:25]
	v_mfma_f32_16x16x32_bf16 v[38:41], v[178:181], v[194:197], v[38:41]
	v_mfma_f32_16x16x32_bf16 v[38:41], v[174:177], v[190:193], v[38:41]
	v_mfma_f32_16x16x32_bf16 v[54:57], v[174:177], v[182:185], v[54:57]
	v_mfma_f32_16x16x32_bf16 v[54:57], v[178:181], v[186:189], v[54:57]
	s_barrier
	v_add_u32_e32 v3, 0x18000, v171
	ds_read_b128 v[134:137], v3
	ds_read_b128 v[138:141], v3 offset:1024
	ds_read_b128 v[142:145], v3 offset:2048
	ds_read_b128 v[146:149], v3 offset:3072
	v_add_u32_e32 v3, 0x1c000, v171
	ds_read_b128 v[150:153], v3
	ds_read_b128 v[154:157], v3 offset:1024
	ds_read_b128 v[174:177], v3 offset:2048
	ds_read_b128 v[178:181], v3 offset:3072
	s_mov_b32 m0, s29
	ds_read_b128 v[182:185], v172 offset:32768
	ds_read_b128 v[186:189], v172 offset:33792
	buffer_load_dwordx4 v1, s[48:51], s97 offen lds
	s_mov_b32 m0, s66
	ds_read_b128 v[190:193], v172 offset:34816
	ds_read_b128 v[194:197], v172 offset:35840
	buffer_load_dwordx4 v167, s[48:51], s97 offen lds
	s_add_i32 s97, s97, 0xc0000
	s_mov_b32 m0, s67
	ds_read_b128 v[198:201], v172 offset:36864
	ds_read_b128 v[202:205], v172 offset:37888
	buffer_load_dwordx4 v1, s[48:51], s97 offen lds
	s_mov_b32 m0, s72
	ds_read_b128 v[206:209], v172 offset:38912
	ds_read_b128 v[210:213], v172 offset:39936
	buffer_load_dwordx4 v167, s[48:51], s97 offen lds
	s_waitcnt vmcnt(8)
	s_waitcnt lgkmcnt(0)
	s_barrier
	s_waitcnt lgkmcnt(0)
	v_mfma_f32_16x16x32_bf16 v[130:133], v[134:137], v[182:185], v[130:133]
	v_mfma_f32_16x16x32_bf16 v[130:133], v[138:141], v[186:189], v[130:133]
	v_mfma_f32_16x16x32_bf16 v[114:117], v[138:141], v[194:197], v[114:117]
	v_mfma_f32_16x16x32_bf16 v[114:117], v[134:137], v[190:193], v[114:117]
	v_mfma_f32_16x16x32_bf16 v[98:101], v[134:137], v[198:201], v[98:101]
	v_mfma_f32_16x16x32_bf16 v[98:101], v[138:141], v[202:205], v[98:101]
	v_mfma_f32_16x16x32_bf16 v[82:85], v[138:141], v[210:213], v[82:85]
	v_mfma_f32_16x16x32_bf16 v[82:85], v[134:137], v[206:209], v[82:85]
	v_mfma_f32_16x16x32_bf16 v[78:81], v[146:149], v[210:213], v[78:81]
	v_mfma_f32_16x16x32_bf16 v[78:81], v[142:145], v[206:209], v[78:81]
	v_mfma_f32_16x16x32_bf16 v[94:97], v[142:145], v[198:201], v[94:97]
	v_mfma_f32_16x16x32_bf16 v[94:97], v[146:149], v[202:205], v[94:97]
	v_mfma_f32_16x16x32_bf16 v[110:113], v[146:149], v[194:197], v[110:113]
	v_mfma_f32_16x16x32_bf16 v[110:113], v[142:145], v[190:193], v[110:113]
	v_mfma_f32_16x16x32_bf16 v[126:129], v[142:145], v[182:185], v[126:129]
	v_mfma_f32_16x16x32_bf16 v[126:129], v[146:149], v[186:189], v[126:129]
	v_mfma_f32_16x16x32_bf16 v[122:125], v[150:153], v[182:185], v[122:125]
	v_mfma_f32_16x16x32_bf16 v[122:125], v[154:157], v[186:189], v[122:125]
	v_mfma_f32_16x16x32_bf16 v[106:109], v[154:157], v[194:197], v[106:109]
	v_mfma_f32_16x16x32_bf16 v[106:109], v[150:153], v[190:193], v[106:109]
	v_mfma_f32_16x16x32_bf16 v[90:93], v[150:153], v[198:201], v[90:93]
	v_mfma_f32_16x16x32_bf16 v[90:93], v[154:157], v[202:205], v[90:93]
	v_mfma_f32_16x16x32_bf16 v[74:77], v[154:157], v[210:213], v[74:77]
	v_mfma_f32_16x16x32_bf16 v[74:77], v[150:153], v[206:209], v[74:77]
	v_mfma_f32_16x16x32_bf16 v[70:73], v[178:181], v[210:213], v[70:73]
	v_mfma_f32_16x16x32_bf16 v[70:73], v[174:177], v[206:209], v[70:73]
	v_mfma_f32_16x16x32_bf16 v[86:89], v[174:177], v[198:201], v[86:89]
	v_mfma_f32_16x16x32_bf16 v[86:89], v[178:181], v[202:205], v[86:89]
	v_mfma_f32_16x16x32_bf16 v[102:105], v[178:181], v[194:197], v[102:105]
	v_mfma_f32_16x16x32_bf16 v[102:105], v[174:177], v[190:193], v[102:105]
	v_mfma_f32_16x16x32_bf16 v[118:121], v[174:177], v[182:185], v[118:121]
	v_mfma_f32_16x16x32_bf16 v[118:121], v[178:181], v[186:189], v[118:121]
	s_barrier
	s_mov_b32 m0, s74
	s_add_i32 s97, s96, 0x80
	ds_read_b128 v[182:185], v172 offset:49152
	ds_read_b128 v[186:189], v172 offset:50176
	buffer_load_dwordx4 v166, s[68:71], s97 offen lds
	s_mov_b32 m0, s75
	ds_read_b128 v[190:193], v172 offset:51200
	ds_read_b128 v[194:197], v172 offset:52224
	buffer_load_dwordx4 v168, s[68:71], s97 offen lds
	s_add_i32 s96, s96, 0xc0080
	s_mov_b32 m0, s77
	ds_read_b128 v[198:201], v172 offset:53248
	ds_read_b128 v[202:205], v172 offset:54272
	buffer_load_dwordx4 v166, s[68:71], s96 offen lds
	s_mov_b32 m0, s78
	ds_read_b128 v[206:209], v172 offset:55296
	ds_read_b128 v[210:213], v172 offset:56320
	buffer_load_dwordx4 v168, s[68:71], s96 offen lds
	s_waitcnt vmcnt(6)
	s_waitcnt lgkmcnt(0)
	s_barrier
	s_waitcnt lgkmcnt(0)
	v_mfma_f32_16x16x32_bf16 v[66:69], v[134:137], v[182:185], v[66:69]
	v_mfma_f32_16x16x32_bf16 v[66:69], v[138:141], v[186:189], v[66:69]
	v_mfma_f32_16x16x32_bf16 v[50:53], v[138:141], v[194:197], v[50:53]
	v_mfma_f32_16x16x32_bf16 v[50:53], v[134:137], v[190:193], v[50:53]
	v_mfma_f32_16x16x32_bf16 v[34:37], v[134:137], v[198:201], v[34:37]
	v_mfma_f32_16x16x32_bf16 v[34:37], v[138:141], v[202:205], v[34:37]
	v_mfma_f32_16x16x32_bf16 v[18:21], v[138:141], v[210:213], v[18:21]
	v_mfma_f32_16x16x32_bf16 v[18:21], v[134:137], v[206:209], v[18:21]
	v_mfma_f32_16x16x32_bf16 v[14:17], v[146:149], v[210:213], v[14:17]
	v_mfma_f32_16x16x32_bf16 v[14:17], v[142:145], v[206:209], v[14:17]
	v_mfma_f32_16x16x32_bf16 v[30:33], v[142:145], v[198:201], v[30:33]
	v_mfma_f32_16x16x32_bf16 v[30:33], v[146:149], v[202:205], v[30:33]
	v_mfma_f32_16x16x32_bf16 v[46:49], v[146:149], v[194:197], v[46:49]
	v_mfma_f32_16x16x32_bf16 v[46:49], v[142:145], v[190:193], v[46:49]
	v_mfma_f32_16x16x32_bf16 v[62:65], v[142:145], v[182:185], v[62:65]
	v_mfma_f32_16x16x32_bf16 v[62:65], v[146:149], v[186:189], v[62:65]
	v_mfma_f32_16x16x32_bf16 v[58:61], v[150:153], v[182:185], v[58:61]
	v_mfma_f32_16x16x32_bf16 v[58:61], v[154:157], v[186:189], v[58:61]
	v_mfma_f32_16x16x32_bf16 v[42:45], v[154:157], v[194:197], v[42:45]
	v_mfma_f32_16x16x32_bf16 v[42:45], v[150:153], v[190:193], v[42:45]
	v_mfma_f32_16x16x32_bf16 v[26:29], v[150:153], v[198:201], v[26:29]
	v_mfma_f32_16x16x32_bf16 v[26:29], v[154:157], v[202:205], v[26:29]
	v_mfma_f32_16x16x32_bf16 v[8:11], v[150:153], v[206:209], v[10:13]
	v_mfma_f32_16x16x32_bf16 v[10:13], v[154:157], v[210:213], v[8:11]
	v_mfma_f32_16x16x32_bf16 v[4:7], v[174:177], v[206:209], v[4:7]
	v_mfma_f32_16x16x32_bf16 v[6:9], v[178:181], v[210:213], v[4:7]
	v_mfma_f32_16x16x32_bf16 v[22:25], v[174:177], v[198:201], v[22:25]
	v_mfma_f32_16x16x32_bf16 v[22:25], v[178:181], v[202:205], v[22:25]
	v_mfma_f32_16x16x32_bf16 v[38:41], v[178:181], v[194:197], v[38:41]
	v_mfma_f32_16x16x32_bf16 v[38:41], v[174:177], v[190:193], v[38:41]
	v_mfma_f32_16x16x32_bf16 v[54:57], v[174:177], v[182:185], v[54:57]
	v_mfma_f32_16x16x32_bf16 v[54:57], v[178:181], v[186:189], v[54:57]
	s_barrier
	s_add_i32 s92, s92, 2
	s_addk_i32 s95, 0x100
	s_addk_i32 s94, 0x100
	s_addk_i32 s93, 0xff00
	s_cmp_ge_u32 s92, s62
	s_cbranch_scc0 .LBB0_528
	s_branch .LBB0_523
.LBB0_529:
	s_setprio 0
	s_and_b64 vcc, exec, s[10:11]
	s_cbranch_vccz .LBB0_531
	s_barrier

.LBB0_604:
	s_add_i32 s11, s59, 0x100
	s_lshl_b32 s9, s78, 20
	s_and_b64 s[80:81], s[4:5], exec
	s_cselect_b32 s79, s9, s64
	s_lshl_b32 s10, s77, 20
	s_and_b64 s[80:81], s[4:5], exec
	s_cselect_b32 s80, s10, s59
	s_mov_b32 s81, -2
	s_mov_b32 s82, 0
	v_readfirstlane_b32 s98, v0
	s_nop 0
	s_bitcmp0_b32 s98, 8
	s_cbranch_scc0 .Lprio_2
	s_setprio 1
.Lprio_2:
.LBB0_605:
	v_add_u32_e32 v141, 0x10000, v139
	ds_read_b128 v[142:145], v141
	ds_read_b128 v[146:149], v141 offset:1024
	ds_read_b128 v[154:157], v141 offset:2048
	ds_read_b128 v[158:161], v141 offset:3072
	v_add_u32_e32 v141, 0x14000, v139
	ds_read_b128 v[162:165], v141
	ds_read_b128 v[166:169], v141 offset:1024
	ds_read_b128 v[170:173], v141 offset:2048
	ds_read_b128 v[174:177], v141 offset:3072
	s_add_i32 s47, s64, s82
	s_add_i32 s84, s47, 0x100
	s_add_i32 s83, s11, s82
	s_cmpk_eq_i32 s82, 0xf00
	s_cselect_b32 s83, s80, s83
	s_cselect_b32 s84, s79, s84
	s_add_i32 s85, s47, 0x80
	s_mov_b32 m0, s71
	ds_read_b128 v[178:181], v140
	ds_read_b128 v[182:185], v140 offset:1024
	buffer_load_dwordx4 v135, s[12:15], s85 offen lds
	s_mov_b32 m0, s72
	ds_read_b128 v[186:189], v140 offset:2048
	ds_read_b128 v[190:193], v140 offset:3072
	buffer_load_dwordx4 v137, s[12:15], s85 offen lds
	s_add_i32 s47, s47, 0x80080
	s_mov_b32 m0, s73
	ds_read_b128 v[194:197], v140 offset:4096
	ds_read_b128 v[198:201], v140 offset:5120
	buffer_load_dwordx4 v135, s[12:15], s47 offen lds
	s_mov_b32 m0, s74
	ds_read_b128 v[202:205], v140 offset:6144
	ds_read_b128 v[206:209], v140 offset:7168
	buffer_load_dwordx4 v137, s[12:15], s47 offen lds
	s_waitcnt vmcnt(8)
	s_waitcnt lgkmcnt(0)
	s_barrier
	s_waitcnt lgkmcnt(0)
	v_mfma_f32_16x16x32_bf16 v[126:129], v[142:145], v[178:181], v[126:129]
	v_mfma_f32_16x16x32_bf16 v[126:129], v[146:149], v[182:185], v[126:129]
	v_mfma_f32_16x16x32_bf16 v[110:113], v[146:149], v[190:193], v[110:113]
	v_mfma_f32_16x16x32_bf16 v[110:113], v[142:145], v[186:189], v[110:113]
	v_mfma_f32_16x16x32_bf16 v[94:97], v[142:145], v[194:197], v[94:97]
	v_mfma_f32_16x16x32_bf16 v[94:97], v[146:149], v[198:201], v[94:97]
	v_mfma_f32_16x16x32_bf16 v[78:81], v[146:149], v[206:209], v[78:81]
	v_mfma_f32_16x16x32_bf16 v[78:81], v[142:145], v[202:205], v[78:81]
	v_mfma_f32_16x16x32_bf16 v[74:77], v[158:161], v[206:209], v[74:77]
	v_mfma_f32_16x16x32_bf16 v[74:77], v[154:157], v[202:205], v[74:77]
	v_mfma_f32_16x16x32_bf16 v[90:93], v[154:157], v[194:197], v[90:93]
	v_mfma_f32_16x16x32_bf16 v[90:93], v[158:161], v[198:201], v[90:93]
	v_mfma_f32_16x16x32_bf16 v[106:109], v[158:161], v[190:193], v[106:109]
	v_mfma_f32_16x16x32_bf16 v[106:109], v[154:157], v[186:189], v[106:109]
	v_mfma_f32_16x16x32_bf16 v[122:125], v[154:157], v[178:181], v[122:125]
	v_mfma_f32_16x16x32_bf16 v[122:125], v[158:161], v[182:185], v[122:125]
	v_mfma_f32_16x16x32_bf16 v[118:121], v[162:165], v[178:181], v[118:121]
	v_mfma_f32_16x16x32_bf16 v[118:121], v[166:169], v[182:185], v[118:121]
	v_mfma_f32_16x16x32_bf16 v[102:105], v[166:169], v[190:193], v[102:105]
	v_mfma_f32_16x16x32_bf16 v[102:105], v[162:165], v[186:189], v[102:105]
	v_mfma_f32_16x16x32_bf16 v[86:89], v[162:165], v[194:197], v[86:89]
	v_mfma_f32_16x16x32_bf16 v[86:89], v[166:169], v[198:201], v[86:89]
	v_mfma_f32_16x16x32_bf16 v[70:73], v[166:169], v[206:209], v[70:73]
	v_mfma_f32_16x16x32_bf16 v[70:73], v[162:165], v[202:205], v[70:73]
	v_mfma_f32_16x16x32_bf16 v[66:69], v[174:177], v[206:209], v[66:69]
	v_mfma_f32_16x16x32_bf16 v[66:69], v[170:173], v[202:205], v[66:69]
	v_mfma_f32_16x16x32_bf16 v[82:85], v[170:173], v[194:197], v[82:85]
	v_mfma_f32_16x16x32_bf16 v[82:85], v[174:177], v[198:201], v[82:85]
	v_mfma_f32_16x16x32_bf16 v[98:101], v[174:177], v[190:193], v[98:101]
	v_mfma_f32_16x16x32_bf16 v[98:101], v[170:173], v[186:189], v[98:101]
	v_mfma_f32_16x16x32_bf16 v[114:117], v[170:173], v[178:181], v[114:117]
	v_mfma_f32_16x16x32_bf16 v[114:117], v[174:177], v[182:185], v[114:117]
	s_barrier
	s_mov_b32 m0, s58
	s_mov_b32 s47, s15
	ds_read_b128 v[178:181], v140 offset:16384
	ds_read_b128 v[182:185], v140 offset:17408
	buffer_load_dwordx4 v136, s[44:47], s83 offen lds
	s_mov_b32 m0, s60
	ds_read_b128 v[186:189], v140 offset:18432
	ds_read_b128 v[190:193], v140 offset:19456
	buffer_load_dwordx4 v138, s[44:47], s83 offen lds
	s_add_i32 s85, s83, 0x80000
	s_mov_b32 m0, s61
	ds_read_b128 v[194:197], v140 offset:20480
	ds_read_b128 v[198:201], v140 offset:21504
	buffer_load_dwordx4 v136, s[44:47], s85 offen lds
	s_mov_b32 m0, s62
	ds_read_b128 v[202:205], v140 offset:22528
	ds_read_b128 v[206:209], v140 offset:23552
	buffer_load_dwordx4 v138, s[44:47], s85 offen lds
	s_waitcnt vmcnt(6)
	s_waitcnt lgkmcnt(0)
	s_barrier
	s_waitcnt lgkmcnt(0)
	v_mfma_f32_16x16x32_bf16 v[62:65], v[142:145], v[178:181], v[62:65]
	v_mfma_f32_16x16x32_bf16 v[62:65], v[146:149], v[182:185], v[62:65]
	v_mfma_f32_16x16x32_bf16 v[46:49], v[146:149], v[190:193], v[46:49]
	v_mfma_f32_16x16x32_bf16 v[46:49], v[142:145], v[186:189], v[46:49]
	v_mfma_f32_16x16x32_bf16 v[30:33], v[142:145], v[194:197], v[30:33]
	v_mfma_f32_16x16x32_bf16 v[30:33], v[146:149], v[198:201], v[30:33]
	v_mfma_f32_16x16x32_bf16 v[14:17], v[146:149], v[206:209], v[14:17]
	v_mfma_f32_16x16x32_bf16 v[14:17], v[142:145], v[202:205], v[14:17]
	v_mfma_f32_16x16x32_bf16 v[10:13], v[158:161], v[206:209], v[10:13]
	v_mfma_f32_16x16x32_bf16 v[10:13], v[154:157], v[202:205], v[10:13]
	v_mfma_f32_16x16x32_bf16 v[26:29], v[154:157], v[194:197], v[26:29]
	v_mfma_f32_16x16x32_bf16 v[26:29], v[158:161], v[198:201], v[26:29]
	v_mfma_f32_16x16x32_bf16 v[42:45], v[158:161], v[190:193], v[42:45]
	v_mfma_f32_16x16x32_bf16 v[42:45], v[154:157], v[186:189], v[42:45]
	v_mfma_f32_16x16x32_bf16 v[58:61], v[154:157], v[178:181], v[58:61]
	v_mfma_f32_16x16x32_bf16 v[58:61], v[158:161], v[182:185], v[58:61]
	v_mfma_f32_16x16x32_bf16 v[54:57], v[162:165], v[178:181], v[54:57]
	v_mfma_f32_16x16x32_bf16 v[54:57], v[166:169], v[182:185], v[54:57]
	v_mfma_f32_16x16x32_bf16 v[38:41], v[166:169], v[190:193], v[38:41]
	v_mfma_f32_16x16x32_bf16 v[38:41], v[162:165], v[186:189], v[38:41]
	v_mfma_f32_16x16x32_bf16 v[22:25], v[162:165], v[194:197], v[22:25]
	v_mfma_f32_16x16x32_bf16 v[22:25], v[166:169], v[198:201], v[22:25]
	v_mfma_f32_16x16x32_bf16 v[6:9], v[166:169], v[206:209], v[6:9]
	v_mfma_f32_16x16x32_bf16 v[6:9], v[162:165], v[202:205], v[6:9]
	v_mfma_f32_16x16x32_bf16 v[2:5], v[174:177], v[206:209], v[2:5]
	v_mfma_f32_16x16x32_bf16 v[2:5], v[170:173], v[202:205], v[2:5]
	v_mfma_f32_16x16x32_bf16 v[18:21], v[170:173], v[194:197], v[18:21]
	v_mfma_f32_16x16x32_bf16 v[18:21], v[174:177], v[198:201], v[18:21]
	v_mfma_f32_16x16x32_bf16 v[34:37], v[174:177], v[190:193], v[34:37]
	v_mfma_f32_16x16x32_bf16 v[34:37], v[170:173], v[186:189], v[34:37]
	v_mfma_f32_16x16x32_bf16 v[50:53], v[170:173], v[178:181], v[50:53]
	v_mfma_f32_16x16x32_bf16 v[50:53], v[174:177], v[182:185], v[50:53]
	s_barrier
	v_add_u32_e32 v141, 0x18000, v139
	ds_read_b128 v[142:145], v141
	ds_read_b128 v[146:149], v141 offset:1024
	ds_read_b128 v[154:157], v141 offset:2048
	ds_read_b128 v[158:161], v141 offset:3072
	v_add_u32_e32 v141, 0x1c000, v139
	ds_read_b128 v[162:165], v141
	ds_read_b128 v[166:169], v141 offset:1024
	ds_read_b128 v[170:173], v141 offset:2048
	ds_read_b128 v[174:177], v141 offset:3072
	s_mov_b32 m0, s51
	ds_read_b128 v[178:181], v140 offset:32768
	ds_read_b128 v[182:185], v140 offset:33792
	buffer_load_dwordx4 v135, s[12:15], s84 offen lds
	s_mov_b32 m0, s63
	ds_read_b128 v[186:189], v140 offset:34816
	ds_read_b128 v[190:193], v140 offset:35840
	buffer_load_dwordx4 v137, s[12:15], s84 offen lds
	s_add_i32 s84, s84, 0x80000
	s_mov_b32 m0, s65
	ds_read_b128 v[194:197], v140 offset:36864
	ds_read_b128 v[198:201], v140 offset:37888
	buffer_load_dwordx4 v135, s[12:15], s84 offen lds
	s_mov_b32 m0, s66
	ds_read_b128 v[202:205], v140 offset:38912
	ds_read_b128 v[206:209], v140 offset:39936
	buffer_load_dwordx4 v137, s[12:15], s84 offen lds
	s_waitcnt vmcnt(8)
	s_waitcnt lgkmcnt(0)
	s_barrier
	s_waitcnt lgkmcnt(0)
	v_mfma_f32_16x16x32_bf16 v[126:129], v[142:145], v[178:181], v[126:129]
	v_mfma_f32_16x16x32_bf16 v[126:129], v[146:149], v[182:185], v[126:129]
	v_mfma_f32_16x16x32_bf16 v[110:113], v[146:149], v[190:193], v[110:113]
	v_mfma_f32_16x16x32_bf16 v[110:113], v[142:145], v[186:189], v[110:113]
	v_mfma_f32_16x16x32_bf16 v[94:97], v[142:145], v[194:197], v[94:97]
	v_mfma_f32_16x16x32_bf16 v[94:97], v[146:149], v[198:201], v[94:97]
	v_mfma_f32_16x16x32_bf16 v[78:81], v[146:149], v[206:209], v[78:81]
	v_mfma_f32_16x16x32_bf16 v[78:81], v[142:145], v[202:205], v[78:81]
	v_mfma_f32_16x16x32_bf16 v[74:77], v[158:161], v[206:209], v[74:77]
	v_mfma_f32_16x16x32_bf16 v[74:77], v[154:157], v[202:205], v[74:77]
	v_mfma_f32_16x16x32_bf16 v[90:93], v[154:157], v[194:197], v[90:93]
	v_mfma_f32_16x16x32_bf16 v[90:93], v[158:161], v[198:201], v[90:93]
	v_mfma_f32_16x16x32_bf16 v[106:109], v[158:161], v[190:193], v[106:109]
	v_mfma_f32_16x16x32_bf16 v[106:109], v[154:157], v[186:189], v[106:109]
	v_mfma_f32_16x16x32_bf16 v[122:125], v[154:157], v[178:181], v[122:125]
	v_mfma_f32_16x16x32_bf16 v[122:125], v[158:161], v[182:185], v[122:125]
	v_mfma_f32_16x16x32_bf16 v[118:121], v[162:165], v[178:181], v[118:121]
	v_mfma_f32_16x16x32_bf16 v[118:121], v[166:169], v[182:185], v[118:121]
	v_mfma_f32_16x16x32_bf16 v[102:105], v[166:169], v[190:193], v[102:105]
	v_mfma_f32_16x16x32_bf16 v[102:105], v[162:165], v[186:189], v[102:105]
	v_mfma_f32_16x16x32_bf16 v[86:89], v[162:165], v[194:197], v[86:89]
	v_mfma_f32_16x16x32_bf16 v[86:89], v[166:169], v[198:201], v[86:89]
	v_mfma_f32_16x16x32_bf16 v[70:73], v[166:169], v[206:209], v[70:73]
	v_mfma_f32_16x16x32_bf16 v[70:73], v[162:165], v[202:205], v[70:73]
	v_mfma_f32_16x16x32_bf16 v[66:69], v[174:177], v[206:209], v[66:69]
	v_mfma_f32_16x16x32_bf16 v[66:69], v[170:173], v[202:205], v[66:69]
	v_mfma_f32_16x16x32_bf16 v[82:85], v[170:173], v[194:197], v[82:85]
	v_mfma_f32_16x16x32_bf16 v[82:85], v[174:177], v[198:201], v[82:85]
	v_mfma_f32_16x16x32_bf16 v[98:101], v[174:177], v[190:193], v[98:101]
	v_mfma_f32_16x16x32_bf16 v[98:101], v[170:173], v[186:189], v[98:101]
	v_mfma_f32_16x16x32_bf16 v[114:117], v[170:173], v[178:181], v[114:117]
	v_mfma_f32_16x16x32_bf16 v[114:117], v[174:177], v[182:185], v[114:117]
	s_barrier
	s_mov_b32 m0, s67
	s_or_b32 s84, s83, 0x80
	ds_read_b128 v[178:181], v140 offset:49152
	ds_read_b128 v[182:185], v140 offset:50176
	buffer_load_dwordx4 v136, s[44:47], s84 offen lds
	s_mov_b32 m0, s68
	ds_read_b128 v[186:189], v140 offset:51200
	ds_read_b128 v[190:193], v140 offset:52224
	buffer_load_dwordx4 v138, s[44:47], s84 offen lds
	s_add_i32 s83, s83, 0x80080
	s_mov_b32 m0, s69
	ds_read_b128 v[194:197], v140 offset:53248
	ds_read_b128 v[198:201], v140 offset:54272
	buffer_load_dwordx4 v136, s[44:47], s83 offen lds
	s_mov_b32 m0, s70
	ds_read_b128 v[202:205], v140 offset:55296
	ds_read_b128 v[206:209], v140 offset:56320
	buffer_load_dwordx4 v138, s[44:47], s83 offen lds
	s_waitcnt vmcnt(6)
	s_waitcnt lgkmcnt(0)
	s_barrier
	s_waitcnt lgkmcnt(0)
	v_mfma_f32_16x16x32_bf16 v[62:65], v[142:145], v[178:181], v[62:65]
	v_mfma_f32_16x16x32_bf16 v[62:65], v[146:149], v[182:185], v[62:65]
	v_mfma_f32_16x16x32_bf16 v[46:49], v[146:149], v[190:193], v[46:49]
	v_mfma_f32_16x16x32_bf16 v[46:49], v[142:145], v[186:189], v[46:49]
	v_mfma_f32_16x16x32_bf16 v[30:33], v[142:145], v[194:197], v[30:33]
	v_mfma_f32_16x16x32_bf16 v[30:33], v[146:149], v[198:201], v[30:33]
	v_mfma_f32_16x16x32_bf16 v[14:17], v[146:149], v[206:209], v[14:17]
	v_mfma_f32_16x16x32_bf16 v[14:17], v[142:145], v[202:205], v[14:17]
	v_mfma_f32_16x16x32_bf16 v[10:13], v[158:161], v[206:209], v[10:13]
	v_mfma_f32_16x16x32_bf16 v[10:13], v[154:157], v[202:205], v[10:13]
	v_mfma_f32_16x16x32_bf16 v[26:29], v[154:157], v[194:197], v[26:29]
	v_mfma_f32_16x16x32_bf16 v[26:29], v[158:161], v[198:201], v[26:29]
	v_mfma_f32_16x16x32_bf16 v[42:45], v[158:161], v[190:193], v[42:45]
	v_mfma_f32_16x16x32_bf16 v[42:45], v[154:157], v[186:189], v[42:45]
	v_mfma_f32_16x16x32_bf16 v[58:61], v[154:157], v[178:181], v[58:61]
	v_mfma_f32_16x16x32_bf16 v[58:61], v[158:161], v[182:185], v[58:61]
	v_mfma_f32_16x16x32_bf16 v[54:57], v[162:165], v[178:181], v[54:57]
	v_mfma_f32_16x16x32_bf16 v[54:57], v[166:169], v[182:185], v[54:57]
	v_mfma_f32_16x16x32_bf16 v[38:41], v[166:169], v[190:193], v[38:41]
	v_mfma_f32_16x16x32_bf16 v[38:41], v[162:165], v[186:189], v[38:41]
	v_mfma_f32_16x16x32_bf16 v[22:25], v[162:165], v[194:197], v[22:25]
	v_mfma_f32_16x16x32_bf16 v[22:25], v[166:169], v[198:201], v[22:25]
	v_mfma_f32_16x16x32_bf16 v[6:9], v[166:169], v[206:209], v[6:9]
	v_mfma_f32_16x16x32_bf16 v[6:9], v[162:165], v[202:205], v[6:9]
	v_mfma_f32_16x16x32_bf16 v[2:5], v[174:177], v[206:209], v[2:5]
	v_mfma_f32_16x16x32_bf16 v[2:5], v[170:173], v[202:205], v[2:5]
	v_mfma_f32_16x16x32_bf16 v[18:21], v[170:173], v[194:197], v[18:21]
	v_mfma_f32_16x16x32_bf16 v[18:21], v[174:177], v[198:201], v[18:21]
	v_mfma_f32_16x16x32_bf16 v[34:37], v[174:177], v[190:193], v[34:37]
	v_mfma_f32_16x16x32_bf16 v[34:37], v[170:173], v[186:189], v[34:37]
	v_mfma_f32_16x16x32_bf16 v[50:53], v[170:173], v[178:181], v[50:53]
	v_mfma_f32_16x16x32_bf16 v[50:53], v[174:177], v[182:185], v[50:53]
	s_barrier
	s_add_i32 s81, s81, 2
	s_addk_i32 s82, 0x100
	s_cmp_gt_u32 s81, 29
	s_cbranch_scc0 .LBB0_605
	s_setprio 0
	s_andn2_b64 vcc, exec, s[4:5]
	s_cbranch_vccnz .LBB0_597
	v_mov_b32_e32 v2, 0
	s_mov_b32 s42, s77
	s_mov_b32 s3, s78
	s_mov_b32 s59, s10
	s_mov_b32 s64, s9
	s_mov_b32 s75, s8
	v_mov_b32_e32 v3, v2
	v_mov_b32_e32 v4, v2
	v_mov_b32_e32 v5, v2
	v_mov_b32_e32 v6, v2
	v_mov_b32_e32 v7, v2
	v_mov_b32_e32 v8, v2
	v_mov_b32_e32 v9, v2
	v_mov_b32_e32 v18, v2
	v_mov_b32_e32 v19, v2
	v_mov_b32_e32 v20, v2
	v_mov_b32_e32 v21, v2
	v_mov_b32_e32 v22, v2
	v_mov_b32_e32 v23, v2
	v_mov_b32_e32 v24, v2
	v_mov_b32_e32 v25, v2
	v_mov_b32_e32 v34, v2
	v_mov_b32_e32 v35, v2
	v_mov_b32_e32 v36, v2
	v_mov_b32_e32 v37, v2
	v_mov_b32_e32 v38, v2
	v_mov_b32_e32 v39, v2
	v_mov_b32_e32 v40, v2
	v_mov_b32_e32 v41, v2
	v_mov_b32_e32 v50, v2
	v_mov_b32_e32 v51, v2
	v_mov_b32_e32 v52, v2
	v_mov_b32_e32 v53, v2
	v_mov_b32_e32 v54, v2
	v_mov_b32_e32 v55, v2
	v_mov_b32_e32 v56, v2
	v_mov_b32_e32 v57, v2
	v_mov_b32_e32 v10, v2
	v_mov_b32_e32 v11, v2
	v_mov_b32_e32 v12, v2
	v_mov_b32_e32 v13, v2
	v_mov_b32_e32 v14, v2
	v_mov_b32_e32 v15, v2
	v_mov_b32_e32 v16, v2
	v_mov_b32_e32 v17, v2
	v_mov_b32_e32 v26, v2
	v_mov_b32_e32 v27, v2
	v_mov_b32_e32 v28, v2
	v_mov_b32_e32 v29, v2
	v_mov_b32_e32 v30, v2
	v_mov_b32_e32 v31, v2
	v_mov_b32_e32 v32, v2
	v_mov_b32_e32 v33, v2
	v_mov_b32_e32 v42, v2
	v_mov_b32_e32 v43, v2
	v_mov_b32_e32 v44, v2
	v_mov_b32_e32 v45, v2
	v_mov_b32_e32 v46, v2
	v_mov_b32_e32 v47, v2
	v_mov_b32_e32 v48, v2
	v_mov_b32_e32 v49, v2
	v_mov_b32_e32 v58, v2
	v_mov_b32_e32 v59, v2
	v_mov_b32_e32 v60, v2
	v_mov_b32_e32 v61, v2
	v_mov_b32_e32 v62, v2
	v_mov_b32_e32 v63, v2
	v_mov_b32_e32 v64, v2
	v_mov_b32_e32 v65, v2
	v_mov_b32_e32 v66, v2
	v_mov_b32_e32 v67, v2
	v_mov_b32_e32 v68, v2
	v_mov_b32_e32 v69, v2
	v_mov_b32_e32 v70, v2
	v_mov_b32_e32 v71, v2
	v_mov_b32_e32 v72, v2
	v_mov_b32_e32 v73, v2
	v_mov_b32_e32 v82, v2
	v_mov_b32_e32 v83, v2
	v_mov_b32_e32 v84, v2
	v_mov_b32_e32 v85, v2
	v_mov_b32_e32 v86, v2
	v_mov_b32_e32 v87, v2
	v_mov_b32_e32 v88, v2
	v_mov_b32_e32 v89, v2
	v_mov_b32_e32 v98, v2
	v_mov_b32_e32 v99, v2
	v_mov_b32_e32 v100, v2
	v_mov_b32_e32 v101, v2
	v_mov_b32_e32 v102, v2
	v_mov_b32_e32 v103, v2
	v_mov_b32_e32 v104, v2
	v_mov_b32_e32 v105, v2
	v_mov_b32_e32 v114, v2
	v_mov_b32_e32 v115, v2
	v_mov_b32_e32 v116, v2
	v_mov_b32_e32 v117, v2
	v_mov_b32_e32 v118, v2
	v_mov_b32_e32 v119, v2
	v_mov_b32_e32 v120, v2
	v_mov_b32_e32 v121, v2
	v_mov_b32_e32 v74, v2
	v_mov_b32_e32 v75, v2
	v_mov_b32_e32 v76, v2
	v_mov_b32_e32 v77, v2
	v_mov_b32_e32 v78, v2
	v_mov_b32_e32 v79, v2
	v_mov_b32_e32 v80, v2
	v_mov_b32_e32 v81, v2
	v_mov_b32_e32 v90, v2
	v_mov_b32_e32 v91, v2
	v_mov_b32_e32 v92, v2
	v_mov_b32_e32 v93, v2
	v_mov_b32_e32 v94, v2
	v_mov_b32_e32 v95, v2
	v_mov_b32_e32 v96, v2
	v_mov_b32_e32 v97, v2
	v_mov_b32_e32 v106, v2
	v_mov_b32_e32 v107, v2
	v_mov_b32_e32 v108, v2
	v_mov_b32_e32 v109, v2
	v_mov_b32_e32 v110, v2
	v_mov_b32_e32 v111, v2
	v_mov_b32_e32 v112, v2
	v_mov_b32_e32 v113, v2
	v_mov_b32_e32 v122, v2
	v_mov_b32_e32 v123, v2
	v_mov_b32_e32 v124, v2
	v_mov_b32_e32 v125, v2
	v_mov_b32_e32 v126, v2
	v_mov_b32_e32 v127, v2
	v_mov_b32_e32 v128, v2
	v_mov_b32_e32 v129, v2
	s_branch .LBB0_597

.LBB0_821:
	s_lshl_b32 s88, s87, 20
	s_and_b64 s[10:11], s[8:9], exec
	s_cselect_b32 s10, s88, s68
	s_lshl_b32 s89, s86, 19
	s_and_b64 s[92:93], s[8:9], exec
	v_mov_b32_e32 v2, 0
	s_cselect_b32 s11, s89, s67
	s_addk_i32 s67, 0x100
	s_add_i32 s68, s68, 0x80080
	s_mov_b32 s69, -2
	v_mov_b32_e32 v3, v2
	v_mov_b32_e32 v4, v2
	v_mov_b32_e32 v5, v2
	v_mov_b32_e32 v6, v2
	v_mov_b32_e32 v7, v2
	v_mov_b32_e32 v8, v2
	s_waitcnt vmcnt(38)
	v_mov_b32_e32 v9, v2
	v_mov_b32_e32 v10, v2
	s_waitcnt vmcnt(36)
	v_mov_b32_e32 v11, v2
	v_mov_b32_e32 v12, v2
	s_waitcnt vmcnt(34)
	v_mov_b32_e32 v13, v2
	s_waitcnt vmcnt(31)
	v_mov_b32_e32 v18, v2
	s_waitcnt vmcnt(28)
	v_mov_b32_e32 v19, v2
	v_mov_b32_e32 v20, v2
	s_waitcnt vmcnt(26)
	v_mov_b32_e32 v21, v2
	v_mov_b32_e32 v14, v2
	v_mov_b32_e32 v15, v2
	v_mov_b32_e32 v16, v2
	v_mov_b32_e32 v17, v2
	v_mov_b32_e32 v22, v2
	s_waitcnt vmcnt(24)
	v_mov_b32_e32 v23, v2
	v_mov_b32_e32 v24, v2
	s_waitcnt vmcnt(22)
	v_mov_b32_e32 v25, v2
	v_mov_b32_e32 v50, v2
	v_mov_b32_e32 v51, v2
	v_mov_b32_e32 v52, v2
	v_mov_b32_e32 v53, v2
	v_mov_b32_e32 v54, v2
	v_mov_b32_e32 v55, v2
	v_mov_b32_e32 v56, v2
	v_mov_b32_e32 v57, v2
	v_mov_b32_e32 v26, v2
	s_waitcnt vmcnt(20)
	v_mov_b32_e32 v27, v2
	v_mov_b32_e32 v28, v2
	s_waitcnt vmcnt(18)
	v_mov_b32_e32 v29, v2
	v_mov_b32_e32 v30, v2
	s_waitcnt vmcnt(16)
	v_mov_b32_e32 v31, v2
	v_mov_b32_e32 v32, v2
	v_mov_b32_e32 v33, v2
	v_mov_b32_e32 v34, v2
	v_mov_b32_e32 v35, v2
	v_mov_b32_e32 v36, v2
	v_mov_b32_e32 v37, v2
	v_mov_b32_e32 v42, v2
	v_mov_b32_e32 v43, v2
	v_mov_b32_e32 v44, v2
	v_mov_b32_e32 v45, v2
	v_mov_b32_e32 v38, v2
	v_mov_b32_e32 v39, v2
	v_mov_b32_e32 v40, v2
	v_mov_b32_e32 v41, v2
	v_mov_b32_e32 v46, v2
	v_mov_b32_e32 v47, v2
	v_mov_b32_e32 v48, v2
	v_mov_b32_e32 v49, v2
	v_mov_b32_e32 v58, v2
	v_mov_b32_e32 v59, v2
	v_mov_b32_e32 v60, v2
	v_mov_b32_e32 v61, v2
	v_mov_b32_e32 v62, v2
	v_mov_b32_e32 v63, v2
	v_mov_b32_e32 v64, v2
	v_mov_b32_e32 v65, v2
	v_mov_b32_e32 v130, v2
	v_mov_b32_e32 v131, v2
	v_mov_b32_e32 v132, v2
	v_mov_b32_e32 v133, v2
	v_mov_b32_e32 v134, v2
	v_mov_b32_e32 v135, v2
	v_mov_b32_e32 v136, v2
	v_mov_b32_e32 v137, v2
	v_mov_b32_e32 v138, v2
	v_mov_b32_e32 v139, v2
	v_mov_b32_e32 v140, v2
	v_mov_b32_e32 v141, v2
	v_mov_b32_e32 v146, v2
	v_mov_b32_e32 v147, v2
	v_mov_b32_e32 v148, v2
	v_mov_b32_e32 v149, v2
	v_mov_b32_e32 v142, v2
	v_mov_b32_e32 v143, v2
	v_mov_b32_e32 v144, v2
	v_mov_b32_e32 v145, v2
	v_mov_b32_e32 v150, v2
	v_mov_b32_e32 v151, v2
	v_mov_b32_e32 v152, v2
	v_mov_b32_e32 v153, v2
	v_mov_b32_e32 v178, v2
	v_mov_b32_e32 v179, v2
	v_mov_b32_e32 v180, v2
	v_mov_b32_e32 v181, v2
	v_mov_b32_e32 v182, v2
	v_mov_b32_e32 v183, v2
	v_mov_b32_e32 v184, v2
	v_mov_b32_e32 v185, v2
	v_mov_b32_e32 v154, v2
	v_mov_b32_e32 v155, v2
	v_mov_b32_e32 v156, v2
	v_mov_b32_e32 v157, v2
	v_mov_b32_e32 v158, v2
	v_mov_b32_e32 v159, v2
	v_mov_b32_e32 v160, v2
	v_mov_b32_e32 v161, v2
	v_mov_b32_e32 v162, v2
	v_mov_b32_e32 v163, v2
	v_mov_b32_e32 v164, v2
	v_mov_b32_e32 v165, v2
	v_mov_b32_e32 v170, v2
	v_mov_b32_e32 v171, v2
	v_mov_b32_e32 v172, v2
	v_mov_b32_e32 v173, v2
	v_mov_b32_e32 v166, v2
	v_mov_b32_e32 v167, v2
	v_mov_b32_e32 v168, v2
	v_mov_b32_e32 v169, v2
	v_mov_b32_e32 v174, v2
	v_mov_b32_e32 v175, v2
	v_mov_b32_e32 v176, v2
	v_mov_b32_e32 v177, v2
	v_mov_b32_e32 v186, v2
	v_mov_b32_e32 v187, v2
	v_mov_b32_e32 v188, v2
	v_mov_b32_e32 v189, v2
	v_mov_b32_e32 v190, v2
	v_mov_b32_e32 v191, v2
	v_mov_b32_e32 v192, v2
	v_mov_b32_e32 v193, v2
	v_readfirstlane_b32 s98, v0
	s_nop 0
	s_bitcmp0_b32 s98, 8
	s_cbranch_scc0 .Lprio_3
	s_setprio 1
.Lprio_3:
.LBB0_822:
	ds_read_b128 v[66:69], v242
	ds_read_b128 v[70:73], v242 offset:1024
	ds_read_b128 v[74:77], v242 offset:2048
	ds_read_b128 v[78:81], v242 offset:3072
	ds_read_b128 v[82:85], v243
	ds_read_b128 v[86:89], v243 offset:1024
	ds_read_b128 v[90:93], v243 offset:2048
	ds_read_b128 v[94:97], v243 offset:3072
	s_add_i32 s43, s68, 0xfff80080
	s_cmp_eq_u32 s69, 28
	s_cselect_b32 s91, s11, s67
	s_cselect_b32 s92, s10, s43
	s_add_i32 s43, s68, 0xfff80000
	s_mov_b32 m0, s79
	ds_read_b128 v[98:101], v244
	ds_read_b128 v[102:105], v244 offset:1024
	buffer_load_dwordx4 v1, s[48:51], s43 offen lds
	s_mov_b32 m0, s80
	ds_read_b128 v[106:109], v244 offset:2048
	ds_read_b128 v[110:113], v244 offset:3072
	buffer_load_dwordx4 v236, s[48:51], s43 offen lds
	s_mov_b32 m0, s81
	ds_read_b128 v[114:117], v244 offset:4096
	ds_read_b128 v[118:121], v244 offset:5120
	buffer_load_dwordx4 v1, s[48:51], s68 offen lds
	s_mov_b32 m0, s82
	ds_read_b128 v[122:125], v244 offset:6144
	ds_read_b128 v[126:129], v244 offset:7168
	buffer_load_dwordx4 v236, s[48:51], s68 offen lds
	s_waitcnt vmcnt(8)
	s_waitcnt lgkmcnt(0)
	s_barrier
	s_waitcnt lgkmcnt(0)
	v_mfma_f32_16x16x32_bf16 v[190:193], v[66:69], v[98:101], v[190:193]
	v_mfma_f32_16x16x32_bf16 v[190:193], v[70:73], v[102:105], v[190:193]
	v_mfma_f32_16x16x32_bf16 v[174:177], v[70:73], v[110:113], v[174:177]
	v_mfma_f32_16x16x32_bf16 v[174:177], v[66:69], v[106:109], v[174:177]
	v_mfma_f32_16x16x32_bf16 v[170:173], v[66:69], v[114:117], v[170:173]
	v_mfma_f32_16x16x32_bf16 v[170:173], v[70:73], v[118:121], v[170:173]
	v_mfma_f32_16x16x32_bf16 v[158:161], v[70:73], v[126:129], v[158:161]
	v_mfma_f32_16x16x32_bf16 v[158:161], v[66:69], v[122:125], v[158:161]
	v_mfma_f32_16x16x32_bf16 v[154:157], v[78:81], v[126:129], v[154:157]
	v_mfma_f32_16x16x32_bf16 v[154:157], v[74:77], v[122:125], v[154:157]
	v_mfma_f32_16x16x32_bf16 v[162:165], v[74:77], v[114:117], v[162:165]
	v_mfma_f32_16x16x32_bf16 v[162:165], v[78:81], v[118:121], v[162:165]
	v_mfma_f32_16x16x32_bf16 v[166:169], v[78:81], v[110:113], v[166:169]
	v_mfma_f32_16x16x32_bf16 v[166:169], v[74:77], v[106:109], v[166:169]
	v_mfma_f32_16x16x32_bf16 v[186:189], v[74:77], v[98:101], v[186:189]
	v_mfma_f32_16x16x32_bf16 v[186:189], v[78:81], v[102:105], v[186:189]
	v_mfma_f32_16x16x32_bf16 v[182:185], v[82:85], v[98:101], v[182:185]
	v_mfma_f32_16x16x32_bf16 v[182:185], v[86:89], v[102:105], v[182:185]
	v_mfma_f32_16x16x32_bf16 v[98:101], v[90:93], v[98:101], v[178:181]
	v_mfma_f32_16x16x32_bf16 v[98:101], v[94:97], v[102:105], v[98:101]
	v_mfma_f32_16x16x32_bf16 v[102:105], v[82:85], v[106:109], v[150:153]
	v_mfma_f32_16x16x32_bf16 v[102:105], v[86:89], v[110:113], v[102:105]
	v_mfma_f32_16x16x32_bf16 v[106:109], v[90:93], v[106:109], v[142:145]
	v_mfma_f32_16x16x32_bf16 v[106:109], v[94:97], v[110:113], v[106:109]
	v_mfma_f32_16x16x32_bf16 v[110:113], v[82:85], v[114:117], v[146:149]
	v_mfma_f32_16x16x32_bf16 v[110:113], v[86:89], v[118:121], v[110:113]
	v_mfma_f32_16x16x32_bf16 v[114:117], v[90:93], v[114:117], v[138:141]
	v_mfma_f32_16x16x32_bf16 v[114:117], v[94:97], v[118:121], v[114:117]
	v_mfma_f32_16x16x32_bf16 v[118:121], v[82:85], v[122:125], v[134:137]
	v_mfma_f32_16x16x32_bf16 v[118:121], v[86:89], v[126:129], v[118:121]
	v_mfma_f32_16x16x32_bf16 v[122:125], v[90:93], v[122:125], v[130:133]
	v_mfma_f32_16x16x32_bf16 v[122:125], v[94:97], v[126:129], v[122:125]
	s_barrier
	s_mov_b32 m0, s29
	s_mov_b32 s43, s51
	ds_read_b128 v[126:129], v244 offset:16384
	ds_read_b128 v[130:133], v244 offset:17408
	buffer_load_dwordx4 v227, s[40:43], s91 offen lds
	s_mov_b32 m0, s35
	ds_read_b128 v[134:137], v244 offset:18432
	ds_read_b128 v[138:141], v244 offset:19456
	buffer_load_dwordx4 v237, s[40:43], s91 offen lds
	s_add_i32 s93, s91, 0x1600000
	s_mov_b32 m0, s63
	ds_read_b128 v[142:145], v244 offset:20480
	ds_read_b128 v[146:149], v244 offset:21504
	buffer_load_dwordx4 v227, s[40:43], s93 offen lds
	s_mov_b32 m0, s65
	ds_read_b128 v[150:153], v244 offset:22528
	ds_read_b128 v[178:181], v244 offset:23552
	buffer_load_dwordx4 v237, s[40:43], s93 offen lds
	s_waitcnt vmcnt(6)
	s_waitcnt lgkmcnt(0)
	s_barrier
	s_waitcnt lgkmcnt(0)
	v_mfma_f32_16x16x32_bf16 v[62:65], v[66:69], v[126:129], v[62:65]
	v_mfma_f32_16x16x32_bf16 v[62:65], v[70:73], v[130:133], v[62:65]
	v_mfma_f32_16x16x32_bf16 v[46:49], v[70:73], v[138:141], v[46:49]
	v_mfma_f32_16x16x32_bf16 v[46:49], v[66:69], v[134:137], v[46:49]
	v_mfma_f32_16x16x32_bf16 v[42:45], v[66:69], v[142:145], v[42:45]
	v_mfma_f32_16x16x32_bf16 v[42:45], v[70:73], v[146:149], v[42:45]
	v_mfma_f32_16x16x32_bf16 v[30:33], v[70:73], v[178:181], v[30:33]
	v_mfma_f32_16x16x32_bf16 v[30:33], v[66:69], v[150:153], v[30:33]
	v_mfma_f32_16x16x32_bf16 v[26:29], v[78:81], v[178:181], v[26:29]
	v_mfma_f32_16x16x32_bf16 v[26:29], v[74:77], v[150:153], v[26:29]
	v_mfma_f32_16x16x32_bf16 v[34:37], v[74:77], v[142:145], v[34:37]
	v_mfma_f32_16x16x32_bf16 v[34:37], v[78:81], v[146:149], v[34:37]
	v_mfma_f32_16x16x32_bf16 v[38:41], v[78:81], v[138:141], v[38:41]
	v_mfma_f32_16x16x32_bf16 v[38:41], v[74:77], v[134:137], v[38:41]
	v_mfma_f32_16x16x32_bf16 v[58:61], v[74:77], v[126:129], v[58:61]
	v_mfma_f32_16x16x32_bf16 v[58:61], v[78:81], v[130:133], v[58:61]
	v_mfma_f32_16x16x32_bf16 v[54:57], v[82:85], v[126:129], v[54:57]
	v_mfma_f32_16x16x32_bf16 v[54:57], v[86:89], v[130:133], v[54:57]
	v_mfma_f32_16x16x32_bf16 v[22:25], v[86:89], v[138:141], v[22:25]
	v_mfma_f32_16x16x32_bf16 v[22:25], v[82:85], v[134:137], v[22:25]
	v_mfma_f32_16x16x32_bf16 v[18:21], v[82:85], v[142:145], v[18:21]
	v_mfma_f32_16x16x32_bf16 v[18:21], v[86:89], v[146:149], v[18:21]
	v_mfma_f32_16x16x32_bf16 v[6:9], v[86:89], v[178:181], v[6:9]
	v_mfma_f32_16x16x32_bf16 v[6:9], v[82:85], v[150:153], v[6:9]
	v_mfma_f32_16x16x32_bf16 v[2:5], v[94:97], v[178:181], v[2:5]
	v_mfma_f32_16x16x32_bf16 v[2:5], v[90:93], v[150:153], v[2:5]
	v_mfma_f32_16x16x32_bf16 v[10:13], v[90:93], v[142:145], v[10:13]
	v_mfma_f32_16x16x32_bf16 v[10:13], v[94:97], v[146:149], v[10:13]
	v_mfma_f32_16x16x32_bf16 v[14:17], v[94:97], v[138:141], v[14:17]
	v_mfma_f32_16x16x32_bf16 v[14:17], v[90:93], v[134:137], v[14:17]
	v_mfma_f32_16x16x32_bf16 v[50:53], v[90:93], v[126:129], v[50:53]
	v_mfma_f32_16x16x32_bf16 v[50:53], v[94:97], v[130:133], v[50:53]
	s_barrier
	ds_read_b128 v[66:69], v245
	ds_read_b128 v[70:73], v245 offset:1024
	ds_read_b128 v[74:77], v245 offset:2048
	ds_read_b128 v[78:81], v245 offset:3072
	ds_read_b128 v[82:85], v246
	ds_read_b128 v[86:89], v246 offset:1024
	ds_read_b128 v[90:93], v246 offset:2048
	ds_read_b128 v[94:97], v246 offset:3072
	s_mov_b32 m0, s3
	ds_read_b128 v[126:129], v244 offset:32768
	ds_read_b128 v[130:133], v244 offset:33792
	buffer_load_dwordx4 v1, s[48:51], s92 offen lds
	s_mov_b32 m0, s70
	ds_read_b128 v[134:137], v244 offset:34816
	ds_read_b128 v[138:141], v244 offset:35840
	buffer_load_dwordx4 v236, s[48:51], s92 offen lds
	s_add_i32 s92, s92, 0x80000
	s_mov_b32 m0, s71
	ds_read_b128 v[194:197], v244 offset:36864
	ds_read_b128 v[198:201], v244 offset:37888
	buffer_load_dwordx4 v1, s[48:51], s92 offen lds
	s_mov_b32 m0, s72
	ds_read_b128 v[202:205], v244 offset:38912
	ds_read_b128 v[206:209], v244 offset:39936
	buffer_load_dwordx4 v236, s[48:51], s92 offen lds
	s_waitcnt vmcnt(8)
	s_waitcnt lgkmcnt(0)
	s_barrier
	s_waitcnt lgkmcnt(0)
	v_mfma_f32_16x16x32_bf16 v[142:145], v[66:69], v[126:129], v[190:193]
	v_mfma_f32_16x16x32_bf16 v[190:193], v[70:73], v[130:133], v[142:145]
	v_mfma_f32_16x16x32_bf16 v[142:145], v[74:77], v[126:129], v[186:189]
	v_mfma_f32_16x16x32_bf16 v[186:189], v[78:81], v[130:133], v[142:145]
	v_mfma_f32_16x16x32_bf16 v[142:145], v[66:69], v[134:137], v[174:177]
	v_mfma_f32_16x16x32_bf16 v[174:177], v[70:73], v[138:141], v[142:145]
	v_mfma_f32_16x16x32_bf16 v[142:145], v[74:77], v[134:137], v[166:169]
	v_mfma_f32_16x16x32_bf16 v[166:169], v[78:81], v[138:141], v[142:145]
	v_mfma_f32_16x16x32_bf16 v[142:145], v[66:69], v[194:197], v[170:173]
	v_mfma_f32_16x16x32_bf16 v[170:173], v[70:73], v[198:201], v[142:145]
	v_mfma_f32_16x16x32_bf16 v[142:145], v[74:77], v[194:197], v[162:165]
	v_mfma_f32_16x16x32_bf16 v[162:165], v[78:81], v[198:201], v[142:145]
	v_mfma_f32_16x16x32_bf16 v[142:145], v[66:69], v[202:205], v[158:161]
	v_mfma_f32_16x16x32_bf16 v[158:161], v[70:73], v[206:209], v[142:145]
	v_mfma_f32_16x16x32_bf16 v[142:145], v[74:77], v[202:205], v[154:157]
	v_mfma_f32_16x16x32_bf16 v[154:157], v[78:81], v[206:209], v[142:145]
	v_mfma_f32_16x16x32_bf16 v[98:101], v[90:93], v[126:129], v[98:101]
	v_mfma_f32_16x16x32_bf16 v[178:181], v[94:97], v[130:133], v[98:101]
	v_mfma_f32_16x16x32_bf16 v[142:145], v[82:85], v[126:129], v[182:185]
	v_mfma_f32_16x16x32_bf16 v[182:185], v[86:89], v[130:133], v[142:145]
	v_mfma_f32_16x16x32_bf16 v[98:101], v[82:85], v[134:137], v[102:105]
	v_mfma_f32_16x16x32_bf16 v[150:153], v[86:89], v[138:141], v[98:101]
	v_mfma_f32_16x16x32_bf16 v[98:101], v[90:93], v[134:137], v[106:109]
	v_mfma_f32_16x16x32_bf16 v[142:145], v[94:97], v[138:141], v[98:101]
	v_mfma_f32_16x16x32_bf16 v[98:101], v[82:85], v[194:197], v[110:113]
	v_mfma_f32_16x16x32_bf16 v[146:149], v[86:89], v[198:201], v[98:101]
	v_mfma_f32_16x16x32_bf16 v[98:101], v[90:93], v[194:197], v[114:117]
	v_mfma_f32_16x16x32_bf16 v[138:141], v[94:97], v[198:201], v[98:101]
	v_mfma_f32_16x16x32_bf16 v[98:101], v[82:85], v[202:205], v[118:121]
	v_mfma_f32_16x16x32_bf16 v[134:137], v[86:89], v[206:209], v[98:101]
	v_mfma_f32_16x16x32_bf16 v[98:101], v[90:93], v[202:205], v[122:125]
	v_mfma_f32_16x16x32_bf16 v[130:133], v[94:97], v[206:209], v[98:101]
	s_barrier
	s_mov_b32 m0, s74
	s_or_b32 s92, s91, 0x80
	s_nop 2
	ds_read_b128 v[98:101], v244 offset:49152
	ds_read_b128 v[102:105], v244 offset:50176
	buffer_load_dwordx4 v227, s[40:43], s92 offen lds
	s_mov_b32 m0, s75
	ds_read_b128 v[106:109], v244 offset:51200
	ds_read_b128 v[110:113], v244 offset:52224
	buffer_load_dwordx4 v237, s[40:43], s92 offen lds
	s_add_i32 s91, s91, 0x1600080
	s_mov_b32 m0, s77
	ds_read_b128 v[114:117], v244 offset:53248
	ds_read_b128 v[118:121], v244 offset:54272
	buffer_load_dwordx4 v227, s[40:43], s91 offen lds
	s_mov_b32 m0, s78
	ds_read_b128 v[122:125], v244 offset:55296
	ds_read_b128 v[126:129], v244 offset:56320
	buffer_load_dwordx4 v237, s[40:43], s91 offen lds
	s_waitcnt vmcnt(6)
	s_waitcnt lgkmcnt(0)
	s_barrier
	s_waitcnt lgkmcnt(0)
	v_mfma_f32_16x16x32_bf16 v[62:65], v[66:69], v[98:101], v[62:65]
	v_mfma_f32_16x16x32_bf16 v[62:65], v[70:73], v[102:105], v[62:65]
	v_mfma_f32_16x16x32_bf16 v[46:49], v[70:73], v[110:113], v[46:49]
	v_mfma_f32_16x16x32_bf16 v[46:49], v[66:69], v[106:109], v[46:49]
	v_mfma_f32_16x16x32_bf16 v[42:45], v[66:69], v[114:117], v[42:45]
	v_mfma_f32_16x16x32_bf16 v[42:45], v[70:73], v[118:121], v[42:45]
	v_mfma_f32_16x16x32_bf16 v[30:33], v[70:73], v[126:129], v[30:33]
	v_mfma_f32_16x16x32_bf16 v[30:33], v[66:69], v[122:125], v[30:33]
	v_mfma_f32_16x16x32_bf16 v[26:29], v[78:81], v[126:129], v[26:29]
	v_mfma_f32_16x16x32_bf16 v[26:29], v[74:77], v[122:125], v[26:29]
	v_mfma_f32_16x16x32_bf16 v[34:37], v[74:77], v[114:117], v[34:37]
	v_mfma_f32_16x16x32_bf16 v[34:37], v[78:81], v[118:121], v[34:37]
	v_mfma_f32_16x16x32_bf16 v[38:41], v[78:81], v[110:113], v[38:41]
	v_mfma_f32_16x16x32_bf16 v[38:41], v[74:77], v[106:109], v[38:41]
	v_mfma_f32_16x16x32_bf16 v[58:61], v[74:77], v[98:101], v[58:61]
	v_mfma_f32_16x16x32_bf16 v[58:61], v[78:81], v[102:105], v[58:61]
	v_mfma_f32_16x16x32_bf16 v[54:57], v[82:85], v[98:101], v[54:57]
	v_mfma_f32_16x16x32_bf16 v[54:57], v[86:89], v[102:105], v[54:57]
	v_mfma_f32_16x16x32_bf16 v[22:25], v[86:89], v[110:113], v[22:25]
	v_mfma_f32_16x16x32_bf16 v[22:25], v[82:85], v[106:109], v[22:25]
	v_mfma_f32_16x16x32_bf16 v[18:21], v[82:85], v[114:117], v[18:21]
	v_mfma_f32_16x16x32_bf16 v[18:21], v[86:89], v[118:121], v[18:21]
	v_mfma_f32_16x16x32_bf16 v[6:9], v[86:89], v[126:129], v[6:9]
	v_mfma_f32_16x16x32_bf16 v[6:9], v[82:85], v[122:125], v[6:9]
	v_mfma_f32_16x16x32_bf16 v[2:5], v[94:97], v[126:129], v[2:5]
	v_mfma_f32_16x16x32_bf16 v[2:5], v[90:93], v[122:125], v[2:5]
	v_mfma_f32_16x16x32_bf16 v[10:13], v[90:93], v[114:117], v[10:13]
	v_mfma_f32_16x16x32_bf16 v[10:13], v[94:97], v[118:121], v[10:13]
	v_mfma_f32_16x16x32_bf16 v[14:17], v[94:97], v[110:113], v[14:17]
	v_mfma_f32_16x16x32_bf16 v[14:17], v[90:93], v[106:109], v[14:17]
	v_mfma_f32_16x16x32_bf16 v[50:53], v[90:93], v[98:101], v[50:53]
	v_mfma_f32_16x16x32_bf16 v[50:53], v[94:97], v[102:105], v[50:53]
	s_barrier
	s_add_i32 s69, s69, 2
	s_addk_i32 s67, 0x100
	s_addk_i32 s68, 0x100
	s_cmp_gt_u32 s69, 29
	s_cbranch_scc0 .LBB0_822
	s_setprio 0
	s_and_b64 vcc, exec, s[38:39]
	s_cbranch_vccz .LBB0_825
	s_barrier

.LBB0_998:
	s_mul_i32 s47, s85, 0x2c0000
	s_and_b64 s[4:5], s[6:7], exec
	s_mul_i32 s86, s84, 0x2c0000
	s_cselect_b32 s87, s47, s61
	s_cselect_b32 s88, s86, s63
	s_cmp_gt_i32 s85, 0
	s_cselect_b64 s[4:5], -1, 0
	s_lshl_b32 s89, s85, 2
	v_cndmask_b32_e64 v140, 0, 1.0, s[4:5]
	s_mov_b32 s92, 0
	s_or_b32 s90, s89, 2
	v_mov_b32_e32 v142, v140
	v_mov_b32_e32 v143, v140
	s_lshl_b32 s91, s85, 8
	v_readfirstlane_b32 s98, v0
	s_nop 0
	s_bitcmp0_b32 s98, 8
	s_cbranch_scc0 .Lprio_4
	s_setprio 1
.Lprio_4:
.LBB0_999:
	s_cmpk_eq_i32 s92, 0x56
	s_cselect_b64 s[48:49], -1, 0
	s_and_b64 s[50:51], s[6:7], s[48:49]
	s_andn2_b64 vcc, exec, s[50:51]
	s_cbranch_vccnz .LBB0_1003
	s_mov_b64 s[50:51], 0
	v_mov_b32_e32 v157, v148
	v_mov_b32_e32 v158, v0

.LBB0_1005:
	s_setprio 0
	s_andn2_b64 vcc, exec, s[6:7]
	s_cbranch_vccnz .LBB0_991
	s_nop 0
	v_mov_b32_e32 v2, 0
	s_mov_b32 s10, s84
	s_mov_b32 s3, s85
	s_mov_b32 s63, s86
	s_mov_b32 s61, s47
	s_mov_b32 s81, s46
	v_mov_b32_e32 v3, v2
	v_mov_b32_e32 v4, v2
	v_mov_b32_e32 v5, v2
	v_mov_b32_e32 v6, v2
	v_mov_b32_e32 v7, v2
	v_mov_b32_e32 v8, v2
	v_mov_b32_e32 v9, v2
	v_mov_b32_e32 v18, v2
	v_mov_b32_e32 v19, v2
	v_mov_b32_e32 v20, v2
	v_mov_b32_e32 v21, v2
	v_mov_b32_e32 v22, v2
	v_mov_b32_e32 v23, v2
	v_mov_b32_e32 v24, v2
	v_mov_b32_e32 v25, v2
	v_mov_b32_e32 v34, v2
	v_mov_b32_e32 v35, v2
	v_mov_b32_e32 v36, v2
	v_mov_b32_e32 v37, v2
	v_mov_b32_e32 v38, v2
	v_mov_b32_e32 v39, v2
	v_mov_b32_e32 v40, v2
	v_mov_b32_e32 v41, v2
	v_mov_b32_e32 v50, v2
	v_mov_b32_e32 v51, v2
	v_mov_b32_e32 v52, v2
	v_mov_b32_e32 v53, v2
	v_mov_b32_e32 v54, v2
	v_mov_b32_e32 v55, v2
	v_mov_b32_e32 v56, v2
	v_mov_b32_e32 v57, v2
	v_mov_b32_e32 v10, v2
	v_mov_b32_e32 v11, v2
	v_mov_b32_e32 v12, v2
	v_mov_b32_e32 v13, v2
	v_mov_b32_e32 v14, v2
	v_mov_b32_e32 v15, v2
	v_mov_b32_e32 v16, v2
	v_mov_b32_e32 v17, v2
	v_mov_b32_e32 v26, v2
	v_mov_b32_e32 v27, v2
	v_mov_b32_e32 v28, v2
	v_mov_b32_e32 v29, v2
	v_mov_b32_e32 v30, v2
	v_mov_b32_e32 v31, v2
	v_mov_b32_e32 v32, v2
	v_mov_b32_e32 v33, v2
	v_mov_b32_e32 v42, v2
	v_mov_b32_e32 v43, v2
	v_mov_b32_e32 v44, v2
	v_mov_b32_e32 v45, v2
	v_mov_b32_e32 v46, v2
	v_mov_b32_e32 v47, v2
	v_mov_b32_e32 v48, v2
	v_mov_b32_e32 v49, v2
	v_mov_b32_e32 v58, v2
	v_mov_b32_e32 v59, v2
	v_mov_b32_e32 v60, v2
	v_mov_b32_e32 v61, v2
	v_mov_b32_e32 v62, v2
	v_mov_b32_e32 v63, v2
	v_mov_b32_e32 v64, v2
	v_mov_b32_e32 v65, v2
	v_mov_b32_e32 v66, v2
	v_mov_b32_e32 v67, v2
	v_mov_b32_e32 v68, v2
	v_mov_b32_e32 v69, v2
	v_mov_b32_e32 v70, v2
	v_mov_b32_e32 v71, v2
	v_mov_b32_e32 v72, v2
	v_mov_b32_e32 v73, v2
	v_mov_b32_e32 v82, v2
	v_mov_b32_e32 v83, v2
	v_mov_b32_e32 v84, v2
	v_mov_b32_e32 v85, v2
	v_mov_b32_e32 v86, v2
	v_mov_b32_e32 v87, v2
	v_mov_b32_e32 v88, v2
	v_mov_b32_e32 v89, v2
	v_mov_b32_e32 v98, v2
	v_mov_b32_e32 v99, v2
	v_mov_b32_e32 v100, v2
	v_mov_b32_e32 v101, v2
	v_mov_b32_e32 v102, v2
	v_mov_b32_e32 v103, v2
	v_mov_b32_e32 v104, v2
	v_mov_b32_e32 v105, v2
	v_mov_b32_e32 v114, v2
	v_mov_b32_e32 v115, v2
	v_mov_b32_e32 v116, v2
	v_mov_b32_e32 v117, v2
	v_mov_b32_e32 v118, v2
	v_mov_b32_e32 v119, v2
	v_mov_b32_e32 v120, v2
	v_mov_b32_e32 v121, v2
	v_mov_b32_e32 v74, v2
	v_mov_b32_e32 v75, v2
	v_mov_b32_e32 v76, v2
	v_mov_b32_e32 v77, v2
	v_mov_b32_e32 v78, v2
	v_mov_b32_e32 v79, v2
	v_mov_b32_e32 v80, v2
	v_mov_b32_e32 v81, v2
	v_mov_b32_e32 v90, v2
	v_mov_b32_e32 v91, v2
	v_mov_b32_e32 v92, v2
	v_mov_b32_e32 v93, v2
	v_mov_b32_e32 v94, v2
	v_mov_b32_e32 v95, v2
	v_mov_b32_e32 v96, v2
	v_mov_b32_e32 v97, v2
	v_mov_b32_e32 v106, v2
	v_mov_b32_e32 v107, v2
	v_mov_b32_e32 v108, v2
	v_mov_b32_e32 v109, v2
	v_mov_b32_e32 v110, v2
	v_mov_b32_e32 v111, v2
	v_mov_b32_e32 v112, v2
	v_mov_b32_e32 v113, v2
	v_mov_b32_e32 v122, v2
	v_mov_b32_e32 v123, v2
	v_mov_b32_e32 v124, v2
	v_mov_b32_e32 v125, v2
	v_mov_b32_e32 v126, v2
	v_mov_b32_e32 v127, v2
	v_mov_b32_e32 v128, v2
	v_mov_b32_e32 v129, v2
	s_branch .LBB0_991
